# attention rings: LDS fragment reads of half-step t+1 issued ahead of the MFMAs of half-step t (read-ahead), on top of v33
# speedup vs baseline: 1.0101x; 1.0009x over previous
; template <bool LOCAL>
; __device__ __forceinline__ void attn_unit(const bf16_t* Q, const bf16_t* KT, const bf16_t* VT, bf16_t* O, LAS unsigned char* lds, int b, int h, int r, int w, int tq, int lane) {
;     ...
;     float mx = -INFINITY;
; #pragma unroll
;     for (int i = 0; i < 2 * NP; ++i) mx = fmaxf(mx, fmaxf(fmaxf(s[i][0], s[i][1]), fmaxf(s[i][2], s[i][3])));
;     mx = fmaxf(mx, __shfl_xor(mx, 16)); mx = fmaxf(mx, __shfl_xor(mx, 32));
.LBB9_673:
	s_or_b64 exec, exec, s[34:35]
	v_max_f32_e32 v66, v126, v126
	v_max_f32_e32 v67, v134, v134
	v_max_f32_e32 v66, v67, v66
	v_max_f32_e32 v67, v123, v123
	v_max_f32_e32 v68, v129, v129
	v_max_f32_e32 v67, v68, v67
	v_max3_f32 v66, v133, v132, v66
	v_max3_f32 v67, v128, v127, v67
	v_max3_f32 v66, v66, s16, v67
	v_max_f32_e32 v67, v118, v118
	v_max_f32_e32 v68, v125, v125
	v_max_f32_e32 v67, v68, v67
	v_max_f32_e32 v68, v115, v115
	v_max_f32_e32 v69, v121, v121
	v_max_f32_e32 v68, v69, v68
	v_max3_f32 v67, v124, v122, v67
	v_max3_f32 v68, v120, v119, v68
	v_max3_f32 v66, v66, v67, v68
	v_max_f32_e32 v67, v110, v110
	v_max_f32_e32 v68, v117, v117
	v_max_f32_e32 v67, v68, v67
	v_max_f32_e32 v68, v113, v113
	v_max_f32_e32 v69, v135, v135
	v_max_f32_e32 v68, v69, v68
	v_max3_f32 v67, v116, v114, v67
	v_max3_f32 v68, v112, v111, v68
	v_max3_f32 v66, v66, v67, v68
	v_max_f32_e32 v67, v102, v102
	v_max_f32_e32 v68, v109, v109
	v_max_f32_e32 v67, v68, v67
	v_max_f32_e32 v68, v99, v99
	v_max_f32_e32 v69, v105, v105
	v_max_f32_e32 v68, v69, v68
	v_max3_f32 v67, v108, v107, v67
	v_max3_f32 v68, v104, v103, v68
	v_max3_f32 v66, v66, v67, v68
	v_max_f32_e32 v67, v94, v94
	v_max_f32_e32 v68, v101, v101
	v_max_f32_e32 v67, v68, v67
	v_max_f32_e32 v68, v91, v91
	v_max_f32_e32 v69, v97, v97
	v_max_f32_e32 v68, v69, v68
	v_max3_f32 v67, v100, v98, v67
	v_max3_f32 v68, v96, v95, v68
	v_max3_f32 v66, v66, v67, v68
	v_max_f32_e32 v67, v86, v86
	v_max_f32_e32 v68, v93, v93
	v_max_f32_e32 v67, v68, v67
	v_max_f32_e32 v68, v89, v89
	v_max_f32_e32 v69, v138, v138
	v_max_f32_e32 v68, v69, v68
	v_max3_f32 v67, v92, v90, v67
	v_max3_f32 v68, v88, v87, v68
	v_max3_f32 v66, v66, v67, v68
	v_max_f32_e32 v67, v139, v139
	v_max_f32_e32 v68, v141, v141
	v_max_f32_e32 v67, v68, v67
	v_max_f32_e32 v68, v197, v197
	v_max_f32_e32 v69, v199, v199
	v_max_f32_e32 v68, v69, v68
	v_max3_f32 v67, v137, v136, v67
	v_max3_f32 v68, v195, v140, v68
	v_max3_f32 v66, v66, v67, v68
	v_max_f32_e32 v67, v200, v200
	v_max_f32_e32 v68, v202, v202
	v_max_f32_e32 v67, v68, v67
	v_max_f32_e32 v68, v204, v204
	v_max_f32_e32 v69, v205, v205
	v_max_f32_e32 v68, v69, v68
	v_max3_f32 v67, v198, v196, v67
	v_max3_f32 v68, v203, v201, v68
	v_max3_f32 v66, v66, v67, v68
	v_max_f32_e32 v67, v5, v5
	v_max_f32_e32 v68, v4, v4
	v_max_f32_e32 v67, v68, v67
	v_max_f32_e32 v68, v13, v13
	v_max_f32_e32 v69, v12, v12
	v_max_f32_e32 v68, v69, v68
	v_max3_f32 v67, v2, v3, v67
	v_max3_f32 v68, v10, v11, v68
	v_max3_f32 v66, v66, v67, v68
	v_max_f32_e32 v67, v9, v9
	v_max_f32_e32 v68, v8, v8
	v_max_f32_e32 v67, v68, v67
	v_max_f32_e32 v68, v21, v21
	v_max_f32_e32 v69, v20, v20
	v_max_f32_e32 v68, v69, v68
	v_max3_f32 v67, v6, v7, v67
	v_max3_f32 v68, v18, v19, v68
	v_max3_f32 v66, v66, v67, v68
	v_max_f32_e32 v67, v17, v17
	v_max_f32_e32 v68, v16, v16
	v_max_f32_e32 v67, v68, v67
	v_max_f32_e32 v68, v29, v29
	v_max_f32_e32 v69, v28, v28
	v_max_f32_e32 v68, v69, v68
	v_max3_f32 v67, v14, v15, v67
	v_max3_f32 v68, v26, v27, v68
	v_max3_f32 v66, v66, v67, v68
	v_max_f32_e32 v67, v25, v25
	v_max_f32_e32 v68, v24, v24
	v_max_f32_e32 v67, v68, v67
	v_max_f32_e32 v68, v37, v37
	v_max_f32_e32 v69, v36, v36
	v_max_f32_e32 v68, v69, v68
	v_max3_f32 v67, v22, v23, v67
	v_max3_f32 v68, v34, v35, v68
	v_max3_f32 v66, v66, v67, v68
	v_max_f32_e32 v67, v33, v33
	v_max_f32_e32 v68, v32, v32
	v_max_f32_e32 v67, v68, v67
	v_max_f32_e32 v68, v45, v45
	v_max_f32_e32 v69, v44, v44
	v_max_f32_e32 v68, v69, v68
	v_max3_f32 v67, v30, v31, v67
	v_max3_f32 v68, v42, v43, v68
	v_max3_f32 v66, v66, v67, v68
	v_max_f32_e32 v67, v41, v41
	v_max_f32_e32 v68, v40, v40
	v_max_f32_e32 v67, v68, v67
	v_max_f32_e32 v68, v53, v53
	v_max_f32_e32 v69, v52, v52
	v_max_f32_e32 v68, v69, v68
	v_max3_f32 v67, v38, v39, v67
	v_max3_f32 v68, v50, v51, v68
	v_max3_f32 v66, v66, v67, v68
	v_max_f32_e32 v67, v49, v49
	v_max_f32_e32 v68, v48, v48
	v_max_f32_e32 v67, v68, v67
	v_max_f32_e32 v68, v61, v61
	v_max_f32_e32 v69, v60, v60
	v_max_f32_e32 v68, v69, v68
	v_max3_f32 v67, v46, v47, v67
	v_max3_f32 v68, v58, v59, v68
	v_max3_f32 v66, v66, v67, v68
	v_max_f32_e32 v67, v57, v57
	v_max_f32_e32 v68, v56, v56
	v_max_f32_e32 v67, v68, v67
	v_max_f32_e32 v68, v65, v65
	v_max_f32_e32 v69, v64, v64
	v_max_f32_e32 v68, v69, v68
	v_max3_f32 v67, v54, v55, v67
	v_max3_f32 v68, v62, v63, v68
	v_max3_f32 v66, v66, v67, v68
	ds_bpermute_b32 v67, v181, v66
	v_lshlrev_b64 v[130:131], 11, v[162:163]
	s_waitcnt lgkmcnt(0)
	v_max_f32_e32 v67, v67, v67
	v_max_f32_e32 v66, v66, v67
	ds_bpermute_b32 v67, v182, v66
	s_waitcnt lgkmcnt(0)
; __device__ __forceinline__ unsigned cvt_pk_bf16(float lo, float hi) { unsigned r; asm volatile("v_cvt_pk_bf16_f32 %0, %1, %2" : "=v"(r) : "v"(lo), "v"(hi)); return r; }
; __device__ __forceinline__ float fast_exp2(float x) { return __builtin_amdgcn_exp2f(x); }
; template <bool LOCAL>
; __device__ __forceinline__ void attn_unit(const bf16_t* Q, const bf16_t* KT, const bf16_t* VT, bf16_t* O, LAS unsigned char* lds, int b, int h, int r, int w, int tq, int lane) {
;     ...
;     float sum = 0.f; const float mxl = mx * 1.4426950408889634f;
;     bf16x8 pb[NP];
; #pragma unroll
;     for (int p = 0; p < NP; ++p) { float e[8];
; #pragma unroll
;         for (int f = 0; f < 2; ++f)
; #pragma unroll
;             for (int j = 0; j < 4; ++j) { e[4 * f + j] = fast_exp2(fmaf(s[2 * p + f][j], 1.4426950408889634f, -mxl)); sum += e[4 * f + j]; }
;         u32x4 pw; pw.x = cvt_pk_bf16(e[0], e[1]); pw.y = cvt_pk_bf16(e[2], e[3]); pw.z = cvt_pk_bf16(e[4], e[5]); pw.w = cvt_pk_bf16(e[6], e[7]);
;         pb[p] = __builtin_bit_cast(bf16x8, pw); }
	v_max_f32_e32 v67, v67, v67
	v_max_f32_e32 v66, v66, v67
	v_mul_f32_e32 v106, 0xbfb8aa3b, v66
	v_fmamk_f32 v66, v133, 0x3fb8aa3b, v106
	v_exp_f32_e32 v66, v66
	v_fmamk_f32 v68, v132, 0x3fb8aa3b, v106
	v_exp_f32_e32 v68, v68
	v_fmamk_f32 v69, v134, 0x3fb8aa3b, v106
	v_exp_f32_e32 v69, v69
	v_fmamk_f32 v70, v126, 0x3fb8aa3b, v106
	v_exp_f32_e32 v70, v70
	v_fmamk_f32 v71, v128, 0x3fb8aa3b, v106
	v_add_f32_e32 v67, 0, v66
	v_exp_f32_e32 v71, v71
	v_fmamk_f32 v72, v127, 0x3fb8aa3b, v106
	v_add_f32_e32 v67, v68, v67
	v_exp_f32_e32 v72, v72
	v_fmamk_f32 v73, v129, 0x3fb8aa3b, v106
	v_add_f32_e32 v67, v69, v67
	v_exp_f32_e32 v73, v73
	v_fmamk_f32 v74, v123, 0x3fb8aa3b, v106
	v_add_f32_e32 v67, v70, v67
	v_exp_f32_e32 v74, v74
	v_add_f32_e32 v67, v71, v67
	v_add_f32_e32 v67, v72, v67
	v_add_f32_e32 v67, v73, v67
	v_add_f32_e32 v75, v74, v67
	v_cvt_pk_bf16_f32 v66, v66, v68
	v_cvt_pk_bf16_f32 v67, v69, v70
	v_fmamk_f32 v70, v124, 0x3fb8aa3b, v106
	v_exp_f32_e32 v70, v70
	v_cvt_pk_bf16_f32 v68, v71, v72
	v_fmamk_f32 v72, v122, 0x3fb8aa3b, v106
	v_cvt_pk_bf16_f32 v69, v73, v74
	v_exp_f32_e32 v72, v72
	v_fmamk_f32 v73, v125, 0x3fb8aa3b, v106
	v_exp_f32_e32 v73, v73
	v_fmamk_f32 v74, v118, 0x3fb8aa3b, v106
	v_add_f32_e32 v71, v70, v75
	v_exp_f32_e32 v74, v74
	v_fmamk_f32 v75, v120, 0x3fb8aa3b, v106
	v_exp_f32_e32 v75, v75
	v_fmamk_f32 v76, v119, 0x3fb8aa3b, v106
	v_add_f32_e32 v71, v72, v71
	v_exp_f32_e32 v76, v76
	v_fmamk_f32 v77, v121, 0x3fb8aa3b, v106
	v_add_f32_e32 v71, v73, v71
	v_exp_f32_e32 v77, v77
	v_fmamk_f32 v78, v115, 0x3fb8aa3b, v106
	v_add_f32_e32 v71, v74, v71
	v_exp_f32_e32 v78, v78
	v_add_f32_e32 v71, v75, v71
	v_add_f32_e32 v71, v76, v71
	v_add_f32_e32 v71, v77, v71
	v_add_f32_e32 v79, v78, v71
	v_cvt_pk_bf16_f32 v70, v70, v72
	v_cvt_pk_bf16_f32 v71, v73, v74
	v_fmamk_f32 v74, v116, 0x3fb8aa3b, v106
	v_exp_f32_e32 v74, v74
	v_cvt_pk_bf16_f32 v72, v75, v76
	v_fmamk_f32 v76, v114, 0x3fb8aa3b, v106
	v_cvt_pk_bf16_f32 v73, v77, v78
	v_exp_f32_e32 v76, v76
	v_fmamk_f32 v77, v117, 0x3fb8aa3b, v106
	v_exp_f32_e32 v77, v77
	v_fmamk_f32 v78, v110, 0x3fb8aa3b, v106
	v_add_f32_e32 v75, v74, v79
	v_exp_f32_e32 v78, v78
	v_fmamk_f32 v79, v112, 0x3fb8aa3b, v106
	v_exp_f32_e32 v79, v79
	v_fmamk_f32 v80, v111, 0x3fb8aa3b, v106
	v_add_f32_e32 v75, v76, v75
	v_exp_f32_e32 v80, v80
	v_fmamk_f32 v81, v135, 0x3fb8aa3b, v106
	v_add_f32_e32 v75, v77, v75
	v_exp_f32_e32 v81, v81
	v_fmamk_f32 v82, v113, 0x3fb8aa3b, v106
	v_add_f32_e32 v75, v78, v75
	v_exp_f32_e32 v82, v82
	v_add_f32_e32 v75, v79, v75
	v_add_f32_e32 v75, v80, v75
	v_add_f32_e32 v75, v81, v75
	v_add_f32_e32 v83, v82, v75
	v_cvt_pk_bf16_f32 v74, v74, v76
	v_cvt_pk_bf16_f32 v75, v77, v78
	v_fmamk_f32 v78, v108, 0x3fb8aa3b, v106
	v_exp_f32_e32 v78, v78
	v_cvt_pk_bf16_f32 v76, v79, v80
	v_fmamk_f32 v80, v107, 0x3fb8aa3b, v106
	v_cvt_pk_bf16_f32 v77, v81, v82
	v_exp_f32_e32 v80, v80
	v_fmamk_f32 v81, v109, 0x3fb8aa3b, v106
	v_exp_f32_e32 v81, v81
	v_fmamk_f32 v82, v102, 0x3fb8aa3b, v106
	v_add_f32_e32 v79, v78, v83
	v_exp_f32_e32 v82, v82
	v_fmamk_f32 v83, v104, 0x3fb8aa3b, v106
	v_exp_f32_e32 v83, v83
	v_fmamk_f32 v84, v103, 0x3fb8aa3b, v106
	v_add_f32_e32 v79, v80, v79
	v_exp_f32_e32 v84, v84
	v_fmamk_f32 v85, v105, 0x3fb8aa3b, v106
	v_add_f32_e32 v79, v81, v79
	v_exp_f32_e32 v85, v85
	v_fmamk_f32 v99, v99, 0x3fb8aa3b, v106
	v_add_f32_e32 v79, v82, v79
	v_exp_f32_e32 v99, v99
	v_add_f32_e32 v79, v83, v79
	v_add_f32_e32 v79, v84, v79
	v_add_f32_e32 v79, v85, v79
	v_add_f32_e32 v102, v99, v79
	v_cvt_pk_bf16_f32 v78, v78, v80
	v_cvt_pk_bf16_f32 v79, v81, v82
	v_fmamk_f32 v82, v100, 0x3fb8aa3b, v106
	v_cvt_pk_bf16_f32 v80, v83, v84
	v_exp_f32_e32 v82, v82
	v_fmamk_f32 v84, v98, 0x3fb8aa3b, v106
	v_cvt_pk_bf16_f32 v81, v85, v99
	v_exp_f32_e32 v84, v84
	v_fmamk_f32 v85, v101, 0x3fb8aa3b, v106
	v_exp_f32_e32 v85, v85
	v_fmamk_f32 v94, v94, 0x3fb8aa3b, v106
	v_exp_f32_e32 v94, v94
	v_fmamk_f32 v96, v96, 0x3fb8aa3b, v106
	v_add_f32_e32 v83, v82, v102
	v_exp_f32_e32 v96, v96
	v_fmamk_f32 v95, v95, 0x3fb8aa3b, v106
	v_add_f32_e32 v83, v84, v83
	v_exp_f32_e32 v95, v95
	v_fmamk_f32 v97, v97, 0x3fb8aa3b, v106
	v_add_f32_e32 v83, v85, v83
	v_exp_f32_e32 v97, v97
	v_fmamk_f32 v91, v91, 0x3fb8aa3b, v106
	v_add_f32_e32 v83, v94, v83
	v_exp_f32_e32 v91, v91
	v_add_f32_e32 v83, v96, v83
	v_add_f32_e32 v83, v95, v83
	v_add_f32_e32 v83, v97, v83
	v_add_f32_e32 v98, v91, v83
	v_cvt_pk_bf16_f32 v82, v82, v84
	v_cvt_pk_bf16_f32 v83, v85, v94
	v_cvt_pk_bf16_f32 v84, v96, v95
	v_cvt_pk_bf16_f32 v85, v97, v91
	v_fmamk_f32 v91, v92, 0x3fb8aa3b, v106
	v_exp_f32_e32 v91, v91
	v_fmamk_f32 v90, v90, 0x3fb8aa3b, v106
	v_exp_f32_e32 v90, v90
	v_fmamk_f32 v93, v93, 0x3fb8aa3b, v106
	v_exp_f32_e32 v93, v93
	v_fmamk_f32 v86, v86, 0x3fb8aa3b, v106
	v_exp_f32_e32 v94, v86
	v_add_f32_e32 v92, v91, v98
	v_add_f32_e32 v92, v90, v92
	v_fmamk_f32 v88, v88, 0x3fb8aa3b, v106
	v_add_f32_e32 v92, v93, v92
	v_exp_f32_e32 v88, v88
	v_fmamk_f32 v87, v87, 0x3fb8aa3b, v106
	v_add_f32_e32 v86, v94, v92
	v_exp_f32_e32 v92, v87
	v_fmamk_f32 v87, v138, 0x3fb8aa3b, v106
	v_exp_f32_e32 v95, v87
	v_fmamk_f32 v87, v89, 0x3fb8aa3b, v106
	v_exp_f32_e32 v89, v87
	v_add_f32_e32 v86, v88, v86
	v_add_f32_e32 v86, v92, v86
	v_add_f32_e32 v86, v95, v86
	v_add_f32_e32 v96, v89, v86
	v_cvt_pk_bf16_f32 v86, v91, v90
	v_fmamk_f32 v90, v137, 0x3fb8aa3b, v106
	v_cvt_pk_bf16_f32 v87, v93, v94
	v_cvt_pk_bf16_f32 v88, v88, v92
	v_exp_f32_e32 v90, v90
	v_fmamk_f32 v92, v136, 0x3fb8aa3b, v106
	v_exp_f32_e32 v92, v92
	v_fmamk_f32 v93, v141, 0x3fb8aa3b, v106
	v_exp_f32_e32 v93, v93
	v_fmamk_f32 v94, v139, 0x3fb8aa3b, v106
	v_cvt_pk_bf16_f32 v89, v95, v89
	v_exp_f32_e32 v95, v94
; __device__ __forceinline__ unsigned cvt_pk_bf16(float lo, float hi) { unsigned r; asm volatile("v_cvt_pk_bf16_f32 %0, %1, %2" : "=v"(r) : "v"(lo), "v"(hi)); return r; }
; __device__ __forceinline__ float fast_exp2(float x) { return __builtin_amdgcn_exp2f(x); }
; template <bool LOCAL>
; __device__ __forceinline__ void attn_unit(const bf16_t* Q, const bf16_t* KT, const bf16_t* VT, bf16_t* O, LAS unsigned char* lds, int b, int h, int r, int w, int tq, int lane) {
;     ...
;     float sum = 0.f; const float mxl = mx * 1.4426950408889634f;
;     bf16x8 pb[NP];
; #pragma unroll
;     for (int p = 0; p < NP; ++p) { float e[8];
; #pragma unroll
;         for (int f = 0; f < 2; ++f)
; #pragma unroll
;             for (int j = 0; j < 4; ++j) { e[4 * f + j] = fast_exp2(fmaf(s[2 * p + f][j], 1.4426950408889634f, -mxl)); sum += e[4 * f + j]; }
;         u32x4 pw; pw.x = cvt_pk_bf16(e[0], e[1]); pw.y = cvt_pk_bf16(e[2], e[3]); pw.z = cvt_pk_bf16(e[4], e[5]); pw.w = cvt_pk_bf16(e[6], e[7]);
;         pb[p] = __builtin_bit_cast(bf16x8, pw); }
	v_fmamk_f32 v94, v195, 0x3fb8aa3b, v106
	v_add_f32_e32 v91, v90, v96
	v_exp_f32_e32 v96, v94
	v_fmamk_f32 v94, v140, 0x3fb8aa3b, v106
	v_add_f32_e32 v91, v92, v91
	v_exp_f32_e32 v97, v94
	v_fmamk_f32 v94, v199, 0x3fb8aa3b, v106
	v_add_f32_e32 v91, v93, v91
	v_exp_f32_e32 v98, v94
	v_fmamk_f32 v94, v197, 0x3fb8aa3b, v106
	v_add_f32_e32 v91, v95, v91
	v_exp_f32_e32 v99, v94
	v_cvt_pk_bf16_f32 v94, v90, v92
	v_fmamk_f32 v90, v198, 0x3fb8aa3b, v106
	v_add_f32_e32 v91, v96, v91
	v_exp_f32_e32 v90, v90
	v_fmamk_f32 v92, v196, 0x3fb8aa3b, v106
	v_add_f32_e32 v91, v97, v91
	v_cvt_pk_bf16_f32 v95, v93, v95
	v_exp_f32_e32 v92, v92
	v_fmamk_f32 v93, v202, 0x3fb8aa3b, v106
	v_add_f32_e32 v91, v98, v91
	v_cvt_pk_bf16_f32 v96, v96, v97
	v_cvt_pk_bf16_f32 v97, v98, v99
	v_exp_f32_e32 v93, v93
	v_fmamk_f32 v98, v200, 0x3fb8aa3b, v106
	v_add_f32_e32 v91, v99, v91
	v_exp_f32_e32 v98, v98
	v_fmamk_f32 v99, v203, 0x3fb8aa3b, v106
	v_add_f32_e32 v91, v90, v91
	v_exp_f32_e32 v99, v99
	v_fmamk_f32 v100, v201, 0x3fb8aa3b, v106
	v_add_f32_e32 v91, v92, v91
	v_exp_f32_e32 v100, v100
	v_fmamk_f32 v101, v205, 0x3fb8aa3b, v106
	v_add_f32_e32 v91, v93, v91
	v_exp_f32_e32 v101, v101
	v_fmamk_f32 v102, v204, 0x3fb8aa3b, v106
	v_add_f32_e32 v91, v98, v91
	v_exp_f32_e32 v105, v102
	v_fmamk_f32 v2, v2, 0x3fb8aa3b, v106
	v_add_f32_e32 v91, v99, v91
	v_exp_f32_e32 v2, v2
	v_fmamk_f32 v3, v3, 0x3fb8aa3b, v106
	v_add_f32_e32 v91, v100, v91
	v_exp_f32_e32 v3, v3
	v_fmamk_f32 v4, v4, 0x3fb8aa3b, v106
	v_add_f32_e32 v91, v101, v91
	v_exp_f32_e32 v4, v4
	v_fmamk_f32 v5, v5, 0x3fb8aa3b, v106
	v_add_f32_e32 v91, v105, v91
	v_exp_f32_e32 v5, v5
	v_fmamk_f32 v10, v10, 0x3fb8aa3b, v106
	v_cvt_pk_bf16_f32 v102, v90, v92
	v_add_f32_e32 v90, v2, v91
	v_exp_f32_e32 v10, v10
	v_fmamk_f32 v11, v11, 0x3fb8aa3b, v106
	v_add_f32_e32 v90, v3, v90
	v_exp_f32_e32 v11, v11
	v_fmamk_f32 v12, v12, 0x3fb8aa3b, v106
	v_add_f32_e32 v90, v4, v90
	v_exp_f32_e32 v12, v12
	v_fmamk_f32 v13, v13, 0x3fb8aa3b, v106
	v_cvt_pk_bf16_f32 v103, v93, v98
	v_cvt_pk_bf16_f32 v104, v99, v100
	v_cvt_pk_bf16_f32 v105, v101, v105
	v_add_f32_e32 v90, v5, v90
	v_exp_f32_e32 v13, v13
	v_cvt_pk_bf16_f32 v98, v2, v3
	v_fmamk_f32 v2, v6, 0x3fb8aa3b, v106
	v_add_f32_e32 v90, v10, v90
	v_cvt_pk_bf16_f32 v99, v4, v5
	v_exp_f32_e32 v2, v2
	v_fmamk_f32 v4, v7, 0x3fb8aa3b, v106
	v_add_f32_e32 v90, v11, v90
	v_exp_f32_e32 v4, v4
	v_fmamk_f32 v5, v8, 0x3fb8aa3b, v106
	v_add_f32_e32 v90, v12, v90
	v_exp_f32_e32 v5, v5
	v_fmamk_f32 v6, v9, 0x3fb8aa3b, v106
	v_add_f32_e32 v90, v13, v90
	v_exp_f32_e32 v6, v6
	v_fmamk_f32 v7, v18, 0x3fb8aa3b, v106
	v_add_f32_e32 v3, v2, v90
	v_exp_f32_e32 v7, v7
	v_fmamk_f32 v8, v19, 0x3fb8aa3b, v106
	v_add_f32_e32 v3, v4, v3
	v_exp_f32_e32 v8, v8
	v_fmamk_f32 v9, v20, 0x3fb8aa3b, v106
	v_cvt_pk_bf16_f32 v100, v10, v11
	v_add_f32_e32 v3, v5, v3
	v_exp_f32_e32 v9, v9
	v_fmamk_f32 v10, v21, 0x3fb8aa3b, v106
	v_cvt_pk_bf16_f32 v101, v12, v13
	v_add_f32_e32 v3, v6, v3
	v_exp_f32_e32 v10, v10
	v_cvt_pk_bf16_f32 v90, v2, v4
	v_fmamk_f32 v2, v14, 0x3fb8aa3b, v106
	v_add_f32_e32 v3, v7, v3
	v_exp_f32_e32 v2, v2
	v_fmamk_f32 v4, v15, 0x3fb8aa3b, v106
	v_add_f32_e32 v3, v8, v3
	v_cvt_pk_bf16_f32 v91, v5, v6
	v_exp_f32_e32 v4, v4
	v_fmamk_f32 v5, v16, 0x3fb8aa3b, v106
	v_add_f32_e32 v3, v9, v3
	v_exp_f32_e32 v5, v5
	v_fmamk_f32 v6, v17, 0x3fb8aa3b, v106
	v_add_f32_e32 v3, v10, v3
	v_cvt_pk_bf16_f32 v92, v7, v8
	v_exp_f32_e32 v6, v6
	v_fmamk_f32 v7, v26, 0x3fb8aa3b, v106
	v_add_f32_e32 v3, v2, v3
	v_exp_f32_e32 v7, v7
	v_fmamk_f32 v8, v27, 0x3fb8aa3b, v106
	v_cvt_pk_bf16_f32 v93, v9, v10
	v_add_f32_e32 v3, v4, v3
	v_exp_f32_e32 v8, v8
	v_fmamk_f32 v9, v28, 0x3fb8aa3b, v106
	v_add_f32_e32 v3, v5, v3
	v_exp_f32_e32 v9, v9
	v_fmamk_f32 v10, v29, 0x3fb8aa3b, v106
	v_add_f32_e32 v3, v6, v3
	v_exp_f32_e32 v10, v10
	v_cvt_pk_bf16_f32 v26, v2, v4
	v_fmamk_f32 v2, v22, 0x3fb8aa3b, v106
	v_add_f32_e32 v3, v7, v3
	v_exp_f32_e32 v2, v2
	v_fmamk_f32 v4, v23, 0x3fb8aa3b, v106
	v_add_f32_e32 v3, v8, v3
	v_cvt_pk_bf16_f32 v27, v5, v6
	v_exp_f32_e32 v4, v4
	v_fmamk_f32 v5, v24, 0x3fb8aa3b, v106
	v_add_f32_e32 v3, v9, v3
	v_exp_f32_e32 v5, v5
	v_fmamk_f32 v6, v25, 0x3fb8aa3b, v106
	v_add_f32_e32 v3, v10, v3
	v_cvt_pk_bf16_f32 v28, v7, v8
	v_exp_f32_e32 v6, v6
	v_fmamk_f32 v7, v34, 0x3fb8aa3b, v106
	v_add_f32_e32 v3, v2, v3
	v_exp_f32_e32 v7, v7
	v_fmamk_f32 v8, v35, 0x3fb8aa3b, v106
	v_cvt_pk_bf16_f32 v29, v9, v10
	v_add_f32_e32 v3, v4, v3
	v_exp_f32_e32 v8, v8
	v_fmamk_f32 v9, v36, 0x3fb8aa3b, v106
	v_add_f32_e32 v3, v5, v3
	v_exp_f32_e32 v9, v9
	v_fmamk_f32 v10, v37, 0x3fb8aa3b, v106
	v_add_f32_e32 v3, v6, v3
	v_exp_f32_e32 v13, v10
	v_cvt_pk_bf16_f32 v10, v2, v4
	v_fmamk_f32 v2, v30, 0x3fb8aa3b, v106
	v_add_f32_e32 v3, v7, v3
	v_exp_f32_e32 v2, v2
	v_fmamk_f32 v4, v31, 0x3fb8aa3b, v106
	v_add_f32_e32 v3, v8, v3
	v_cvt_pk_bf16_f32 v11, v5, v6
	v_exp_f32_e32 v4, v4
	v_fmamk_f32 v5, v32, 0x3fb8aa3b, v106
	v_add_f32_e32 v3, v9, v3
	v_exp_f32_e32 v5, v5
	v_fmamk_f32 v6, v33, 0x3fb8aa3b, v106
	v_add_f32_e32 v3, v13, v3
	v_cvt_pk_bf16_f32 v12, v7, v8
	v_exp_f32_e32 v6, v6
	v_fmamk_f32 v7, v42, 0x3fb8aa3b, v106
	v_add_f32_e32 v3, v2, v3
	v_exp_f32_e32 v7, v7
	v_fmamk_f32 v8, v43, 0x3fb8aa3b, v106
	v_cvt_pk_bf16_f32 v13, v9, v13
	v_add_f32_e32 v3, v4, v3
	v_exp_f32_e32 v8, v8
	v_fmamk_f32 v9, v44, 0x3fb8aa3b, v106
	v_add_f32_e32 v3, v5, v3
	v_exp_f32_e32 v9, v9
	v_fmamk_f32 v14, v45, 0x3fb8aa3b, v106
	v_add_f32_e32 v3, v6, v3
	v_exp_f32_e32 v14, v14
	v_add_f32_e32 v3, v7, v3
	v_add_f32_e32 v3, v8, v3
	v_add_f32_e32 v3, v9, v3
	v_add_f32_e32 v15, v14, v3
	v_cvt_pk_bf16_f32 v2, v2, v4
	v_cvt_pk_bf16_f32 v3, v5, v6
	v_fmamk_f32 v6, v38, 0x3fb8aa3b, v106
; #define LAS __attribute__((address_space(3)))
; __device__ __forceinline__ unsigned cvt_pk_bf16(float lo, float hi) { unsigned r; asm volatile("v_cvt_pk_bf16_f32 %0, %1, %2" : "=v"(r) : "v"(lo), "v"(hi)); return r; }
; __device__ __forceinline__ float fast_exp2(float x) { return __builtin_amdgcn_exp2f(x); }
; #define ATT_VLOAD(buf, p) do { const bf16_t* vp_ = vloc + (size_t)((p) * 8 * NH) * 1024; \
;         _Pragma("unroll") for (int df = 0; df < 8; ++df) va[buf][df] = *(const bf16x8*)(vp_ + df * 128); } while (0)
; template <bool LOCAL>
; __device__ __forceinline__ void attn_unit(const bf16_t* Q, const bf16_t* KT, const bf16_t* VT, bf16_t* O, LAS unsigned char* lds, int b, int h, int r, int w, int tq, int lane) {
;     ...
;     for (int p = 0; p < NP; ++p) { float e[8];
; #pragma unroll
;         for (int f = 0; f < 2; ++f)
; #pragma unroll
;             for (int j = 0; j < 4; ++j) { e[4 * f + j] = fast_exp2(fmaf(s[2 * p + f][j], 1.4426950408889634f, -mxl)); sum += e[4 * f + j]; }
;         u32x4 pw; pw.x = cvt_pk_bf16(e[0], e[1]); pw.y = cvt_pk_bf16(e[2], e[3]); pw.z = cvt_pk_bf16(e[4], e[5]); pw.w = cvt_pk_bf16(e[6], e[7]);
;         pb[p] = __builtin_bit_cast(bf16x8, pw); }
;     sum += __shfl_xor(sum, 16); sum += __shfl_xor(sum, 32);
;     f32x4 o[8];
; #pragma unroll
;     for (int df = 0; df < 8; ++df) o[df] = (f32x4){0.f, 0.f, 0.f, 0.f};
;     if (LOCAL) {
;         const bf16_t* vloc = VT + ((size_t)(((rgl >> 3) + g) * NH + h)) * 1024 + q * 8;
;         bf16x8 va[2][8];
;     ...
;         ATT_VLOAD(0, 0);
; #pragma unroll
;         for (int p = 0; p < 8; ++p) {
;             __builtin_amdgcn_s_barrier();
;             if (p + 1 < 8) ATT_VLOAD((p + 1) & 1, p + 1);
;             __builtin_amdgcn_sched_barrier(0);
; #pragma unroll
;             for (int df = 0; df < 8; ++df) o[df] = __builtin_amdgcn_mfma_f32_16x16x32_bf16(va[p & 1][df], pb[p], o[df], 0, 0, 0);
;             __builtin_amdgcn_sched_barrier(0);
;         }
;     ...
;     }
;     {
;         const LAS unsigned char* vl = lds + 65536 + g * 2048 + q * 16;
; #pragma unroll
;         for (int p = 0; p < 8; ++p)
; #pragma unroll
;             for (int df = 0; df < 8; ++df) o[df] = __builtin_amdgcn_mfma_f32_16x16x32_bf16(*(const LAS bf16x8*)(vl + p * 8192 + df * 256), pb[CP + p], o[df], 0, 0, 0);
	v_exp_f32_e32 v6, v6
	v_cvt_pk_bf16_f32 v4, v7, v8
	v_fmamk_f32 v8, v39, 0x3fb8aa3b, v106
	v_cvt_pk_bf16_f32 v5, v9, v14
	v_exp_f32_e32 v8, v8
	v_fmamk_f32 v9, v40, 0x3fb8aa3b, v106
	v_exp_f32_e32 v9, v9
	v_fmamk_f32 v14, v41, 0x3fb8aa3b, v106
	v_add_f32_e32 v7, v6, v15
	v_exp_f32_e32 v14, v14
	v_fmamk_f32 v15, v50, 0x3fb8aa3b, v106
	v_exp_f32_e32 v15, v15
	v_fmamk_f32 v16, v51, 0x3fb8aa3b, v106
	v_add_f32_e32 v7, v8, v7
	v_exp_f32_e32 v16, v16
	v_fmamk_f32 v17, v52, 0x3fb8aa3b, v106
	v_add_f32_e32 v7, v9, v7
	v_exp_f32_e32 v17, v17
	v_fmamk_f32 v18, v53, 0x3fb8aa3b, v106
	v_add_f32_e32 v7, v14, v7
	v_exp_f32_e32 v18, v18
	v_add_f32_e32 v7, v15, v7
	v_add_f32_e32 v7, v16, v7
	v_add_f32_e32 v7, v17, v7
	v_add_f32_e32 v19, v18, v7
	v_cvt_pk_bf16_f32 v6, v6, v8
	v_cvt_pk_bf16_f32 v7, v9, v14
	v_fmamk_f32 v14, v46, 0x3fb8aa3b, v106
	v_exp_f32_e32 v14, v14
	v_cvt_pk_bf16_f32 v8, v15, v16
	v_fmamk_f32 v16, v47, 0x3fb8aa3b, v106
	v_cvt_pk_bf16_f32 v9, v17, v18
	v_exp_f32_e32 v16, v16
	v_fmamk_f32 v17, v48, 0x3fb8aa3b, v106
	v_exp_f32_e32 v17, v17
	v_fmamk_f32 v18, v49, 0x3fb8aa3b, v106
	v_add_f32_e32 v15, v14, v19
	v_exp_f32_e32 v18, v18
	v_fmamk_f32 v19, v58, 0x3fb8aa3b, v106
	v_exp_f32_e32 v19, v19
	v_fmamk_f32 v20, v59, 0x3fb8aa3b, v106
	v_add_f32_e32 v15, v16, v15
	v_exp_f32_e32 v20, v20
	v_fmamk_f32 v21, v60, 0x3fb8aa3b, v106
	v_add_f32_e32 v15, v17, v15
	v_exp_f32_e32 v21, v21
	v_fmamk_f32 v22, v61, 0x3fb8aa3b, v106
	v_add_f32_e32 v15, v18, v15
	v_exp_f32_e32 v22, v22
	v_add_f32_e32 v15, v19, v15
	v_add_f32_e32 v15, v20, v15
	v_add_f32_e32 v15, v21, v15
	v_add_f32_e32 v23, v22, v15
	v_cvt_pk_bf16_f32 v14, v14, v16
	v_cvt_pk_bf16_f32 v15, v17, v18
	v_fmamk_f32 v18, v54, 0x3fb8aa3b, v106
	v_exp_f32_e32 v18, v18
	v_cvt_pk_bf16_f32 v16, v19, v20
	v_fmamk_f32 v20, v55, 0x3fb8aa3b, v106
	v_cvt_pk_bf16_f32 v17, v21, v22
	v_exp_f32_e32 v20, v20
	v_fmamk_f32 v21, v56, 0x3fb8aa3b, v106
	v_exp_f32_e32 v21, v21
	v_fmamk_f32 v22, v57, 0x3fb8aa3b, v106
	v_add_f32_e32 v19, v18, v23
	v_exp_f32_e32 v22, v22
	v_fmamk_f32 v23, v62, 0x3fb8aa3b, v106
	v_exp_f32_e32 v23, v23
	v_fmamk_f32 v24, v63, 0x3fb8aa3b, v106
	v_add_f32_e32 v19, v20, v19
	v_exp_f32_e32 v24, v24
	v_fmamk_f32 v25, v64, 0x3fb8aa3b, v106
	v_add_f32_e32 v19, v21, v19
	v_exp_f32_e32 v25, v25
	v_fmac_f32_e32 v106, 0x3fb8aa3b, v65
	v_add_f32_e32 v19, v22, v19
	v_exp_f32_e32 v30, v106
	v_add_f32_e32 v19, v23, v19
	v_add_f32_e32 v19, v24, v19
	v_add_f32_e32 v19, v25, v19
	v_add_f32_e32 v31, v30, v19
	v_cvt_pk_bf16_f32 v18, v18, v20
	v_cvt_pk_bf16_f32 v19, v21, v22
	ds_bpermute_b32 v22, v181, v31
	v_cvt_pk_bf16_f32 v20, v23, v24
	v_cvt_pk_bf16_f32 v21, v25, v30
	s_waitcnt lgkmcnt(0)
	v_add_f32_e32 v134, v31, v22
	v_add_u32_e32 v22, v194, v165
	v_lshl_or_b32 v22, v22, 4, s72
	v_ashrrev_i32_e32 v23, 31, v22
	v_lshlrev_b64 v[22:23], 11, v[22:23]
	v_lshl_add_u64 v[132:133], v[148:149], 0, v[22:23]
	ds_bpermute_b32 v135, v182, v134
	s_cmp_eq_u32 s53, 0
	s_cbranch_scc0 .Lrg_v_B
	s_waitcnt vmcnt(6)
	s_barrier
	ds_read_b128 v[106:109], v219 offset:0
	ds_read_b128 v[110:113], v219 offset:256
	ds_read_b128 v[114:117], v219 offset:512
	ds_read_b128 v[118:121], v219 offset:768
	s_waitcnt vmcnt(5)
	s_barrier
	s_add_i32 m0, s59, 57344
	v_add_co_u32_e32 v222, vcc, s2, v226
	s_nop 1
	v_addc_co_u32_e32 v223, vcc, 0, v227, vcc
	global_load_lds_dwordx4 v[222:223], off
	ds_read_b128 v[122:125], v219 offset:8192
	ds_read_b128 v[126:129], v219 offset:8448
	ds_read_b128 v[58:61], v219 offset:8704
	ds_read_b128 v[62:65], v219 offset:8960
	s_waitcnt lgkmcnt(4)
	v_mfma_f32_16x16x32_bf16 v[22:25], v[106:109], v[66:69], 0
	v_mfma_f32_16x16x32_bf16 v[30:33], v[110:113], v[66:69], 0
	v_mfma_f32_16x16x32_bf16 v[34:37], v[114:117], v[66:69], 0
	v_mfma_f32_16x16x32_bf16 v[38:41], v[118:121], v[66:69], 0
	s_waitcnt vmcnt(5)
	s_barrier
	s_add_i32 m0, s59, 0
	v_add_co_u32_e32 v222, vcc, s60, v220
	s_nop 1
	v_addc_co_u32_e32 v223, vcc, 0, v221, vcc
	global_load_lds_dwordx4 v[222:223], off
	ds_read_b128 v[106:109], v219 offset:16384
	ds_read_b128 v[110:113], v219 offset:16640
	ds_read_b128 v[114:117], v219 offset:16896
	ds_read_b128 v[118:121], v219 offset:17152
	s_waitcnt lgkmcnt(4)
	v_mfma_f32_16x16x32_bf16 v[42:45], v[122:125], v[66:69], 0
	v_mfma_f32_16x16x32_bf16 v[46:49], v[126:129], v[66:69], 0
	v_mfma_f32_16x16x32_bf16 v[50:53], v[58:61], v[66:69], 0
	v_mfma_f32_16x16x32_bf16 v[54:57], v[62:65], v[66:69], 0
	s_waitcnt vmcnt(5)
	s_barrier
	s_add_i32 m0, s59, 8192
	v_add_co_u32_e32 v222, vcc, s60, v226
	s_nop 1
	v_addc_co_u32_e32 v223, vcc, 0, v227, vcc
	global_load_lds_dwordx4 v[222:223], off
	ds_read_b128 v[122:125], v219 offset:24576
	ds_read_b128 v[126:129], v219 offset:24832
	ds_read_b128 v[58:61], v219 offset:25088
	ds_read_b128 v[62:65], v219 offset:25344
	s_waitcnt lgkmcnt(4)
	v_mfma_f32_16x16x32_bf16 v[22:25], v[106:109], v[70:73], v[22:25]
	v_mfma_f32_16x16x32_bf16 v[30:33], v[110:113], v[70:73], v[30:33]
	v_mfma_f32_16x16x32_bf16 v[34:37], v[114:117], v[70:73], v[34:37]
	v_mfma_f32_16x16x32_bf16 v[38:41], v[118:121], v[70:73], v[38:41]
	s_waitcnt vmcnt(5)
	s_barrier
	s_add_i32 m0, s59, 16384
	v_add_co_u32_e32 v222, vcc, s61, v220
	s_nop 1
	v_addc_co_u32_e32 v223, vcc, 0, v221, vcc
	global_load_lds_dwordx4 v[222:223], off
	ds_read_b128 v[106:109], v219 offset:32768
	ds_read_b128 v[110:113], v219 offset:33024
	ds_read_b128 v[114:117], v219 offset:33280
	ds_read_b128 v[118:121], v219 offset:33536
	s_waitcnt lgkmcnt(4)
	v_mfma_f32_16x16x32_bf16 v[42:45], v[122:125], v[70:73], v[42:45]
	v_mfma_f32_16x16x32_bf16 v[46:49], v[126:129], v[70:73], v[46:49]
	v_mfma_f32_16x16x32_bf16 v[50:53], v[58:61], v[70:73], v[50:53]
	v_mfma_f32_16x16x32_bf16 v[54:57], v[62:65], v[70:73], v[54:57]
	s_waitcnt vmcnt(5)
	s_barrier
; #define LAS __attribute__((address_space(3)))
; #define ATT_VLOAD(buf, p) do { const bf16_t* vp_ = vloc + (size_t)((p) * 8 * NH) * 1024; \
;         _Pragma("unroll") for (int df = 0; df < 8; ++df) va[buf][df] = *(const bf16x8*)(vp_ + df * 128); } while (0)
; template <bool LOCAL>
; __device__ __forceinline__ void attn_unit(const bf16_t* Q, const bf16_t* KT, const bf16_t* VT, bf16_t* O, LAS unsigned char* lds, int b, int h, int r, int w, int tq, int lane) {
;     ...
;     if (LOCAL) {
;         const bf16_t* vloc = VT + ((size_t)(((rgl >> 3) + g) * NH + h)) * 1024 + q * 8;
;         bf16x8 va[2][8];
;     ...
;         ATT_VLOAD(0, 0);
; #pragma unroll
;         for (int p = 0; p < 8; ++p) {
;             __builtin_amdgcn_s_barrier();
;             if (p + 1 < 8) ATT_VLOAD((p + 1) & 1, p + 1);
;             __builtin_amdgcn_sched_barrier(0);
; #pragma unroll
;             for (int df = 0; df < 8; ++df) o[df] = __builtin_amdgcn_mfma_f32_16x16x32_bf16(va[p & 1][df], pb[p], o[df], 0, 0, 0);
;             __builtin_amdgcn_sched_barrier(0);
;         }
;     ...
;     }
;     {
;         const LAS unsigned char* vl = lds + 65536 + g * 2048 + q * 16;
; #pragma unroll
;         for (int p = 0; p < 8; ++p)
; #pragma unroll
;             for (int df = 0; df < 8; ++df) o[df] = __builtin_amdgcn_mfma_f32_16x16x32_bf16(*(const LAS bf16x8*)(vl + p * 8192 + df * 256), pb[CP + p], o[df], 0, 0, 0);
;     }
	s_add_i32 m0, s59, 24576
	v_add_co_u32_e32 v222, vcc, s61, v226
	s_nop 1
	v_addc_co_u32_e32 v223, vcc, 0, v227, vcc
	global_load_lds_dwordx4 v[222:223], off
	ds_read_b128 v[122:125], v219 offset:40960
	ds_read_b128 v[126:129], v219 offset:41216
	ds_read_b128 v[58:61], v219 offset:41472
	ds_read_b128 v[62:65], v219 offset:41728
	s_waitcnt lgkmcnt(4)
	v_mfma_f32_16x16x32_bf16 v[22:25], v[106:109], v[74:77], v[22:25]
	v_mfma_f32_16x16x32_bf16 v[30:33], v[110:113], v[74:77], v[30:33]
	v_mfma_f32_16x16x32_bf16 v[34:37], v[114:117], v[74:77], v[34:37]
	v_mfma_f32_16x16x32_bf16 v[38:41], v[118:121], v[74:77], v[38:41]
	s_waitcnt vmcnt(5)
	s_barrier
	s_add_i32 m0, s59, 32768
	v_add_co_u32_e32 v222, vcc, s17, v220
	s_nop 1
	v_addc_co_u32_e32 v223, vcc, 0, v221, vcc
	global_load_lds_dwordx4 v[222:223], off
	ds_read_b128 v[106:109], v219 offset:49152
	ds_read_b128 v[110:113], v219 offset:49408
	ds_read_b128 v[114:117], v219 offset:49664
	ds_read_b128 v[118:121], v219 offset:49920
	s_waitcnt lgkmcnt(4)
	v_mfma_f32_16x16x32_bf16 v[42:45], v[122:125], v[74:77], v[42:45]
	v_mfma_f32_16x16x32_bf16 v[46:49], v[126:129], v[74:77], v[46:49]
	v_mfma_f32_16x16x32_bf16 v[50:53], v[58:61], v[74:77], v[50:53]
	v_mfma_f32_16x16x32_bf16 v[54:57], v[62:65], v[74:77], v[54:57]
	s_waitcnt vmcnt(5)
	s_barrier
	s_add_i32 m0, s59, 40960
	v_add_co_u32_e32 v222, vcc, s17, v226
	s_nop 1
	v_addc_co_u32_e32 v223, vcc, 0, v227, vcc
	global_load_lds_dwordx4 v[222:223], off
	ds_read_b128 v[122:125], v219 offset:57344
	ds_read_b128 v[126:129], v219 offset:57600
	ds_read_b128 v[58:61], v219 offset:57856
	ds_read_b128 v[62:65], v219 offset:58112
	s_waitcnt lgkmcnt(4)
	v_mfma_f32_16x16x32_bf16 v[22:25], v[106:109], v[78:81], v[22:25]
	v_mfma_f32_16x16x32_bf16 v[30:33], v[110:113], v[78:81], v[30:33]
	v_mfma_f32_16x16x32_bf16 v[34:37], v[114:117], v[78:81], v[34:37]
	v_mfma_f32_16x16x32_bf16 v[38:41], v[118:121], v[78:81], v[38:41]
	s_waitcnt vmcnt(5)
	s_barrier
	s_add_i32 m0, s59, 49152
	v_add_co_u32_e32 v222, vcc, s62, v220
	s_nop 1
	v_addc_co_u32_e32 v223, vcc, 0, v221, vcc
	global_load_lds_dwordx4 v[222:223], off
	ds_read_b128 v[106:109], v219 offset:0
	ds_read_b128 v[110:113], v219 offset:256
	ds_read_b128 v[114:117], v219 offset:512
	ds_read_b128 v[118:121], v219 offset:768
	s_waitcnt lgkmcnt(4)
	v_mfma_f32_16x16x32_bf16 v[42:45], v[122:125], v[78:81], v[42:45]
	v_mfma_f32_16x16x32_bf16 v[46:49], v[126:129], v[78:81], v[46:49]
	v_mfma_f32_16x16x32_bf16 v[50:53], v[58:61], v[78:81], v[50:53]
	v_mfma_f32_16x16x32_bf16 v[54:57], v[62:65], v[78:81], v[54:57]
	s_waitcnt vmcnt(5)
	s_barrier
	s_add_i32 m0, s59, 57344
	v_add_co_u32_e32 v222, vcc, s62, v226
	s_nop 1
	v_addc_co_u32_e32 v223, vcc, 0, v227, vcc
	global_load_lds_dwordx4 v[222:223], off
	ds_read_b128 v[122:125], v219 offset:8192
	ds_read_b128 v[126:129], v219 offset:8448
	ds_read_b128 v[58:61], v219 offset:8704
	ds_read_b128 v[62:65], v219 offset:8960
	s_waitcnt lgkmcnt(4)
	v_mfma_f32_16x16x32_bf16 v[22:25], v[106:109], v[82:85], v[22:25]
	v_mfma_f32_16x16x32_bf16 v[30:33], v[110:113], v[82:85], v[30:33]
	v_mfma_f32_16x16x32_bf16 v[34:37], v[114:117], v[82:85], v[34:37]
	v_mfma_f32_16x16x32_bf16 v[38:41], v[118:121], v[82:85], v[38:41]
	s_waitcnt vmcnt(5)
	s_barrier
	s_cmp_eq_u32 s73, 0
	s_cbranch_scc1 .Lrg_v_A_nd9
	s_add_i32 m0, s59, 0
	v_add_co_u32_e32 v222, vcc, s75, v220
	s_nop 1
	v_addc_co_u32_e32 v223, vcc, 0, v221, vcc
	global_load_lds_dwordx4 v[222:223], off
.Lrg_v_A_nd9:
	ds_read_b128 v[106:109], v219 offset:16384
	ds_read_b128 v[110:113], v219 offset:16640
	ds_read_b128 v[114:117], v219 offset:16896
	ds_read_b128 v[118:121], v219 offset:17152
	s_waitcnt lgkmcnt(4)
	v_mfma_f32_16x16x32_bf16 v[42:45], v[122:125], v[82:85], v[42:45]
	v_mfma_f32_16x16x32_bf16 v[46:49], v[126:129], v[82:85], v[46:49]
	v_mfma_f32_16x16x32_bf16 v[50:53], v[58:61], v[82:85], v[50:53]
	v_mfma_f32_16x16x32_bf16 v[54:57], v[62:65], v[82:85], v[54:57]
	s_waitcnt vmcnt(4)
	s_barrier
	s_cmp_eq_u32 s73, 0
	s_cbranch_scc1 .Lrg_v_A_nd10
	s_add_i32 m0, s59, 8192
	v_add_co_u32_e32 v222, vcc, s75, v226
	s_nop 1
	v_addc_co_u32_e32 v223, vcc, 0, v227, vcc
	global_load_lds_dwordx4 v[222:223], off
.Lrg_v_A_nd10:
	ds_read_b128 v[122:125], v219 offset:24576
	ds_read_b128 v[126:129], v219 offset:24832
	ds_read_b128 v[58:61], v219 offset:25088
	ds_read_b128 v[62:65], v219 offset:25344
	s_waitcnt lgkmcnt(4)
	v_mfma_f32_16x16x32_bf16 v[22:25], v[106:109], v[86:89], v[22:25]
	v_mfma_f32_16x16x32_bf16 v[30:33], v[110:113], v[86:89], v[30:33]
	v_mfma_f32_16x16x32_bf16 v[34:37], v[114:117], v[86:89], v[34:37]
	v_mfma_f32_16x16x32_bf16 v[38:41], v[118:121], v[86:89], v[38:41]
	s_waitcnt vmcnt(3)
	s_barrier
	ds_read_b128 v[106:109], v219 offset:32768
	ds_read_b128 v[110:113], v219 offset:33024
	ds_read_b128 v[114:117], v219 offset:33280
	ds_read_b128 v[118:121], v219 offset:33536
	s_waitcnt lgkmcnt(4)
	v_mfma_f32_16x16x32_bf16 v[42:45], v[122:125], v[86:89], v[42:45]
	v_mfma_f32_16x16x32_bf16 v[46:49], v[126:129], v[86:89], v[46:49]
	v_mfma_f32_16x16x32_bf16 v[50:53], v[58:61], v[86:89], v[50:53]
	v_mfma_f32_16x16x32_bf16 v[54:57], v[62:65], v[86:89], v[54:57]
	s_waitcnt vmcnt(2)
	s_barrier
	ds_read_b128 v[122:125], v219 offset:40960
	ds_read_b128 v[126:129], v219 offset:41216
	ds_read_b128 v[58:61], v219 offset:41472
	ds_read_b128 v[62:65], v219 offset:41728
	s_waitcnt lgkmcnt(4)
	v_mfma_f32_16x16x32_bf16 v[22:25], v[106:109], v[94:97], v[22:25]
	v_mfma_f32_16x16x32_bf16 v[30:33], v[110:113], v[94:97], v[30:33]
	v_mfma_f32_16x16x32_bf16 v[34:37], v[114:117], v[94:97], v[34:37]
	v_mfma_f32_16x16x32_bf16 v[38:41], v[118:121], v[94:97], v[38:41]
	s_waitcnt vmcnt(1)
	s_barrier
	ds_read_b128 v[106:109], v219 offset:49152
	ds_read_b128 v[110:113], v219 offset:49408
	ds_read_b128 v[114:117], v219 offset:49664
	ds_read_b128 v[118:121], v219 offset:49920
	s_waitcnt lgkmcnt(4)
	v_mfma_f32_16x16x32_bf16 v[42:45], v[122:125], v[94:97], v[42:45]
	v_mfma_f32_16x16x32_bf16 v[46:49], v[126:129], v[94:97], v[46:49]
	v_mfma_f32_16x16x32_bf16 v[50:53], v[58:61], v[94:97], v[50:53]
	v_mfma_f32_16x16x32_bf16 v[54:57], v[62:65], v[94:97], v[54:57]
	s_waitcnt vmcnt(0)
	s_barrier
	ds_read_b128 v[122:125], v219 offset:57344
	ds_read_b128 v[126:129], v219 offset:57600
	ds_read_b128 v[58:61], v219 offset:57856
	ds_read_b128 v[62:65], v219 offset:58112
	s_waitcnt lgkmcnt(4)
	v_mfma_f32_16x16x32_bf16 v[22:25], v[106:109], v[102:105], v[22:25]
	v_mfma_f32_16x16x32_bf16 v[30:33], v[110:113], v[102:105], v[30:33]
	v_mfma_f32_16x16x32_bf16 v[34:37], v[114:117], v[102:105], v[34:37]
	v_mfma_f32_16x16x32_bf16 v[38:41], v[118:121], v[102:105], v[38:41]
	s_waitcnt vmcnt(1)
	s_barrier
	s_waitcnt lgkmcnt(0)
	v_mfma_f32_16x16x32_bf16 v[42:45], v[122:125], v[102:105], v[42:45]
	v_mfma_f32_16x16x32_bf16 v[46:49], v[126:129], v[102:105], v[46:49]
	v_mfma_f32_16x16x32_bf16 v[50:53], v[58:61], v[102:105], v[50:53]
	v_mfma_f32_16x16x32_bf16 v[54:57], v[62:65], v[102:105], v[54:57]
	s_cmp_eq_u32 s73, 0
	s_cbranch_scc1 .Lrg_v_A_end
	s_waitcnt vmcnt(0)
	s_barrier

; #define LAS __attribute__((address_space(3)))
; #define ATT_VLOAD(buf, p) do { const bf16_t* vp_ = vloc + (size_t)((p) * 8 * NH) * 1024; \
;         _Pragma("unroll") for (int df = 0; df < 8; ++df) va[buf][df] = *(const bf16x8*)(vp_ + df * 128); } while (0)
; template <bool LOCAL>
; __device__ __forceinline__ void attn_unit(const bf16_t* Q, const bf16_t* KT, const bf16_t* VT, bf16_t* O, LAS unsigned char* lds, int b, int h, int r, int w, int tq, int lane) {
;     ...
;     if (LOCAL) {
;         const bf16_t* vloc = VT + ((size_t)(((rgl >> 3) + g) * NH + h)) * 1024 + q * 8;
;         bf16x8 va[2][8];
;     ...
;         ATT_VLOAD(0, 0);
; #pragma unroll
;         for (int p = 0; p < 8; ++p) {
;             __builtin_amdgcn_s_barrier();
;             if (p + 1 < 8) ATT_VLOAD((p + 1) & 1, p + 1);
;             __builtin_amdgcn_sched_barrier(0);
; #pragma unroll
;             for (int df = 0; df < 8; ++df) o[df] = __builtin_amdgcn_mfma_f32_16x16x32_bf16(va[p & 1][df], pb[p], o[df], 0, 0, 0);
;             __builtin_amdgcn_sched_barrier(0);
;         }
;     ...
;     }
;     {
;         const LAS unsigned char* vl = lds + 65536 + g * 2048 + q * 16;
; #pragma unroll
;         for (int p = 0; p < 8; ++p)
; #pragma unroll
;             for (int df = 0; df < 8; ++df) o[df] = __builtin_amdgcn_mfma_f32_16x16x32_bf16(*(const LAS bf16x8*)(vl + p * 8192 + df * 256), pb[CP + p], o[df], 0, 0, 0);
;     }
.Lrg_v_B:
	s_waitcnt vmcnt(6)
	s_barrier
	s_waitcnt vmcnt(5)
	s_barrier
	s_add_i32 m0, s59, 57344
	v_add_co_u32_e32 v222, vcc, s2, v226
	s_nop 1
	v_addc_co_u32_e32 v223, vcc, 0, v227, vcc
	global_load_lds_dwordx4 v[222:223], off
	s_waitcnt vmcnt(5)
	s_barrier
	s_add_i32 m0, s59, 0
	v_add_co_u32_e32 v222, vcc, s60, v220
	s_nop 1
	v_addc_co_u32_e32 v223, vcc, 0, v221, vcc
	global_load_lds_dwordx4 v[222:223], off
	ds_read_b128 v[106:109], v219 offset:16384
	ds_read_b128 v[110:113], v219 offset:16640
	ds_read_b128 v[114:117], v219 offset:16896
	ds_read_b128 v[118:121], v219 offset:17152
	s_waitcnt vmcnt(5)
	s_barrier
	s_add_i32 m0, s59, 8192
	v_add_co_u32_e32 v222, vcc, s60, v226
	s_nop 1
	v_addc_co_u32_e32 v223, vcc, 0, v227, vcc
	global_load_lds_dwordx4 v[222:223], off
	ds_read_b128 v[122:125], v219 offset:24576
	ds_read_b128 v[126:129], v219 offset:24832
	ds_read_b128 v[58:61], v219 offset:25088
	ds_read_b128 v[62:65], v219 offset:25344
	s_waitcnt lgkmcnt(4)
	v_mfma_f32_16x16x32_bf16 v[22:25], v[106:109], v[66:69], 0
	v_mfma_f32_16x16x32_bf16 v[30:33], v[110:113], v[66:69], 0
	v_mfma_f32_16x16x32_bf16 v[34:37], v[114:117], v[66:69], 0
	v_mfma_f32_16x16x32_bf16 v[38:41], v[118:121], v[66:69], 0
	s_waitcnt vmcnt(5)
	s_barrier
	s_add_i32 m0, s59, 16384
	v_add_co_u32_e32 v222, vcc, s61, v220
	s_nop 1
	v_addc_co_u32_e32 v223, vcc, 0, v221, vcc
	global_load_lds_dwordx4 v[222:223], off
	ds_read_b128 v[106:109], v219 offset:32768
	ds_read_b128 v[110:113], v219 offset:33024
	ds_read_b128 v[114:117], v219 offset:33280
	ds_read_b128 v[118:121], v219 offset:33536
	s_waitcnt lgkmcnt(4)
	v_mfma_f32_16x16x32_bf16 v[42:45], v[122:125], v[66:69], 0
	v_mfma_f32_16x16x32_bf16 v[46:49], v[126:129], v[66:69], 0
	v_mfma_f32_16x16x32_bf16 v[50:53], v[58:61], v[66:69], 0
	v_mfma_f32_16x16x32_bf16 v[54:57], v[62:65], v[66:69], 0
	s_waitcnt vmcnt(5)
	s_barrier
	s_add_i32 m0, s59, 24576
	v_add_co_u32_e32 v222, vcc, s61, v226
	s_nop 1
	v_addc_co_u32_e32 v223, vcc, 0, v227, vcc
	global_load_lds_dwordx4 v[222:223], off
	ds_read_b128 v[122:125], v219 offset:40960
	ds_read_b128 v[126:129], v219 offset:41216
	ds_read_b128 v[58:61], v219 offset:41472
	ds_read_b128 v[62:65], v219 offset:41728
	s_waitcnt lgkmcnt(4)
	v_mfma_f32_16x16x32_bf16 v[22:25], v[106:109], v[70:73], v[22:25]
	v_mfma_f32_16x16x32_bf16 v[30:33], v[110:113], v[70:73], v[30:33]
	v_mfma_f32_16x16x32_bf16 v[34:37], v[114:117], v[70:73], v[34:37]
	v_mfma_f32_16x16x32_bf16 v[38:41], v[118:121], v[70:73], v[38:41]
	s_waitcnt vmcnt(5)
	s_barrier
	s_add_i32 m0, s59, 32768
	v_add_co_u32_e32 v222, vcc, s17, v220
	s_nop 1
	v_addc_co_u32_e32 v223, vcc, 0, v221, vcc
	global_load_lds_dwordx4 v[222:223], off
	ds_read_b128 v[106:109], v219 offset:49152
	ds_read_b128 v[110:113], v219 offset:49408
	ds_read_b128 v[114:117], v219 offset:49664
	ds_read_b128 v[118:121], v219 offset:49920
	s_waitcnt lgkmcnt(4)
	v_mfma_f32_16x16x32_bf16 v[42:45], v[122:125], v[70:73], v[42:45]
	v_mfma_f32_16x16x32_bf16 v[46:49], v[126:129], v[70:73], v[46:49]
	v_mfma_f32_16x16x32_bf16 v[50:53], v[58:61], v[70:73], v[50:53]
	v_mfma_f32_16x16x32_bf16 v[54:57], v[62:65], v[70:73], v[54:57]
	s_waitcnt vmcnt(5)
	s_barrier
	s_add_i32 m0, s59, 40960
	v_add_co_u32_e32 v222, vcc, s17, v226
	s_nop 1
	v_addc_co_u32_e32 v223, vcc, 0, v227, vcc
	global_load_lds_dwordx4 v[222:223], off
	ds_read_b128 v[122:125], v219 offset:57344
	ds_read_b128 v[126:129], v219 offset:57600
	ds_read_b128 v[58:61], v219 offset:57856
	ds_read_b128 v[62:65], v219 offset:58112
	s_waitcnt lgkmcnt(4)
	v_mfma_f32_16x16x32_bf16 v[22:25], v[106:109], v[74:77], v[22:25]
	v_mfma_f32_16x16x32_bf16 v[30:33], v[110:113], v[74:77], v[30:33]
	v_mfma_f32_16x16x32_bf16 v[34:37], v[114:117], v[74:77], v[34:37]
	v_mfma_f32_16x16x32_bf16 v[38:41], v[118:121], v[74:77], v[38:41]
	s_waitcnt vmcnt(5)
	s_barrier
	s_add_i32 m0, s59, 49152
	v_add_co_u32_e32 v222, vcc, s62, v220
	s_nop 1
	v_addc_co_u32_e32 v223, vcc, 0, v221, vcc
	global_load_lds_dwordx4 v[222:223], off
	ds_read_b128 v[106:109], v219 offset:0
	ds_read_b128 v[110:113], v219 offset:256
	ds_read_b128 v[114:117], v219 offset:512
	ds_read_b128 v[118:121], v219 offset:768
	s_waitcnt lgkmcnt(4)
	v_mfma_f32_16x16x32_bf16 v[42:45], v[122:125], v[74:77], v[42:45]
	v_mfma_f32_16x16x32_bf16 v[46:49], v[126:129], v[74:77], v[46:49]
	v_mfma_f32_16x16x32_bf16 v[50:53], v[58:61], v[74:77], v[50:53]
	v_mfma_f32_16x16x32_bf16 v[54:57], v[62:65], v[74:77], v[54:57]
	s_waitcnt vmcnt(5)
	s_barrier
	s_add_i32 m0, s59, 57344
	v_add_co_u32_e32 v222, vcc, s62, v226
	s_nop 1
	v_addc_co_u32_e32 v223, vcc, 0, v227, vcc
	global_load_lds_dwordx4 v[222:223], off
	ds_read_b128 v[122:125], v219 offset:8192
	ds_read_b128 v[126:129], v219 offset:8448
	ds_read_b128 v[58:61], v219 offset:8704
	ds_read_b128 v[62:65], v219 offset:8960
	s_waitcnt lgkmcnt(4)
	v_mfma_f32_16x16x32_bf16 v[22:25], v[106:109], v[78:81], v[22:25]
	v_mfma_f32_16x16x32_bf16 v[30:33], v[110:113], v[78:81], v[30:33]
	v_mfma_f32_16x16x32_bf16 v[34:37], v[114:117], v[78:81], v[34:37]
	v_mfma_f32_16x16x32_bf16 v[38:41], v[118:121], v[78:81], v[38:41]
	s_waitcnt vmcnt(5)
	s_barrier
	s_cmp_eq_u32 s73, 0
	s_cbranch_scc1 .Lrg_v_B_nd9
	s_add_i32 m0, s59, 0
	v_add_co_u32_e32 v222, vcc, s75, v220
	s_nop 1
	v_addc_co_u32_e32 v223, vcc, 0, v221, vcc
	global_load_lds_dwordx4 v[222:223], off
; #define LAS __attribute__((address_space(3)))
; #define ATT_VLOAD(buf, p) do { const bf16_t* vp_ = vloc + (size_t)((p) * 8 * NH) * 1024; \
;         _Pragma("unroll") for (int df = 0; df < 8; ++df) va[buf][df] = *(const bf16x8*)(vp_ + df * 128); } while (0)
; template <bool LOCAL>
; __device__ __forceinline__ void attn_unit(const bf16_t* Q, const bf16_t* KT, const bf16_t* VT, bf16_t* O, LAS unsigned char* lds, int b, int h, int r, int w, int tq, int lane) {
;     ...
;     if (LOCAL) {
;         const bf16_t* vloc = VT + ((size_t)(((rgl >> 3) + g) * NH + h)) * 1024 + q * 8;
;         bf16x8 va[2][8];
;     ...
;         ATT_VLOAD(0, 0);
; #pragma unroll
;         for (int p = 0; p < 8; ++p) {
;             __builtin_amdgcn_s_barrier();
;             if (p + 1 < 8) ATT_VLOAD((p + 1) & 1, p + 1);
;             __builtin_amdgcn_sched_barrier(0);
; #pragma unroll
;             for (int df = 0; df < 8; ++df) o[df] = __builtin_amdgcn_mfma_f32_16x16x32_bf16(va[p & 1][df], pb[p], o[df], 0, 0, 0);
;             __builtin_amdgcn_sched_barrier(0);
;         }
;     ...
;     }
;     {
;         const LAS unsigned char* vl = lds + 65536 + g * 2048 + q * 16;
; #pragma unroll
;         for (int p = 0; p < 8; ++p)
; #pragma unroll
;             for (int df = 0; df < 8; ++df) o[df] = __builtin_amdgcn_mfma_f32_16x16x32_bf16(*(const LAS bf16x8*)(vl + p * 8192 + df * 256), pb[CP + p], o[df], 0, 0, 0);
;     }
.Lrg_v_B_nd9:
	ds_read_b128 v[106:109], v219 offset:16384
	ds_read_b128 v[110:113], v219 offset:16640
	ds_read_b128 v[114:117], v219 offset:16896
	ds_read_b128 v[118:121], v219 offset:17152
	s_waitcnt lgkmcnt(4)
	v_mfma_f32_16x16x32_bf16 v[42:45], v[122:125], v[78:81], v[42:45]
	v_mfma_f32_16x16x32_bf16 v[46:49], v[126:129], v[78:81], v[46:49]
	v_mfma_f32_16x16x32_bf16 v[50:53], v[58:61], v[78:81], v[50:53]
	v_mfma_f32_16x16x32_bf16 v[54:57], v[62:65], v[78:81], v[54:57]
	s_waitcnt vmcnt(4)
	s_barrier
	s_cmp_eq_u32 s73, 0
	s_cbranch_scc1 .Lrg_v_B_nd10
	s_add_i32 m0, s59, 8192
	v_add_co_u32_e32 v222, vcc, s75, v226
	s_nop 1
	v_addc_co_u32_e32 v223, vcc, 0, v227, vcc
	global_load_lds_dwordx4 v[222:223], off
.Lrg_v_B_nd10:
	ds_read_b128 v[122:125], v219 offset:24576
	ds_read_b128 v[126:129], v219 offset:24832
	ds_read_b128 v[58:61], v219 offset:25088
	ds_read_b128 v[62:65], v219 offset:25344
	s_waitcnt lgkmcnt(4)
	v_mfma_f32_16x16x32_bf16 v[22:25], v[106:109], v[82:85], v[22:25]
	v_mfma_f32_16x16x32_bf16 v[30:33], v[110:113], v[82:85], v[30:33]
	v_mfma_f32_16x16x32_bf16 v[34:37], v[114:117], v[82:85], v[34:37]
	v_mfma_f32_16x16x32_bf16 v[38:41], v[118:121], v[82:85], v[38:41]
	s_waitcnt vmcnt(3)
	s_barrier
	ds_read_b128 v[106:109], v219 offset:32768
	ds_read_b128 v[110:113], v219 offset:33024
	ds_read_b128 v[114:117], v219 offset:33280
	ds_read_b128 v[118:121], v219 offset:33536
	s_waitcnt lgkmcnt(4)
	v_mfma_f32_16x16x32_bf16 v[42:45], v[122:125], v[82:85], v[42:45]
	v_mfma_f32_16x16x32_bf16 v[46:49], v[126:129], v[82:85], v[46:49]
	v_mfma_f32_16x16x32_bf16 v[50:53], v[58:61], v[82:85], v[50:53]
	v_mfma_f32_16x16x32_bf16 v[54:57], v[62:65], v[82:85], v[54:57]
	s_waitcnt vmcnt(2)
	s_barrier
	ds_read_b128 v[122:125], v219 offset:40960
	ds_read_b128 v[126:129], v219 offset:41216
	ds_read_b128 v[58:61], v219 offset:41472
	ds_read_b128 v[62:65], v219 offset:41728
	s_waitcnt lgkmcnt(4)
	v_mfma_f32_16x16x32_bf16 v[22:25], v[106:109], v[86:89], v[22:25]
	v_mfma_f32_16x16x32_bf16 v[30:33], v[110:113], v[86:89], v[30:33]
	v_mfma_f32_16x16x32_bf16 v[34:37], v[114:117], v[86:89], v[34:37]
	v_mfma_f32_16x16x32_bf16 v[38:41], v[118:121], v[86:89], v[38:41]
	s_waitcnt vmcnt(1)
	s_barrier
	ds_read_b128 v[106:109], v219 offset:49152
	ds_read_b128 v[110:113], v219 offset:49408
	ds_read_b128 v[114:117], v219 offset:49664
	ds_read_b128 v[118:121], v219 offset:49920
	s_waitcnt lgkmcnt(4)
	v_mfma_f32_16x16x32_bf16 v[42:45], v[122:125], v[86:89], v[42:45]
	v_mfma_f32_16x16x32_bf16 v[46:49], v[126:129], v[86:89], v[46:49]
	v_mfma_f32_16x16x32_bf16 v[50:53], v[58:61], v[86:89], v[50:53]
	v_mfma_f32_16x16x32_bf16 v[54:57], v[62:65], v[86:89], v[54:57]
	s_waitcnt vmcnt(0)
	s_barrier
	ds_read_b128 v[122:125], v219 offset:57344
	ds_read_b128 v[126:129], v219 offset:57600
	ds_read_b128 v[58:61], v219 offset:57856
	ds_read_b128 v[62:65], v219 offset:58112
	s_waitcnt lgkmcnt(4)
	v_mfma_f32_16x16x32_bf16 v[22:25], v[106:109], v[94:97], v[22:25]
	v_mfma_f32_16x16x32_bf16 v[30:33], v[110:113], v[94:97], v[30:33]
	v_mfma_f32_16x16x32_bf16 v[34:37], v[114:117], v[94:97], v[34:37]
	v_mfma_f32_16x16x32_bf16 v[38:41], v[118:121], v[94:97], v[38:41]
	s_waitcnt vmcnt(1)
	s_barrier
	ds_read_b128 v[106:109], v219 offset:0
	ds_read_b128 v[110:113], v219 offset:256
	ds_read_b128 v[114:117], v219 offset:512
	ds_read_b128 v[118:121], v219 offset:768
	s_waitcnt lgkmcnt(4)
	v_mfma_f32_16x16x32_bf16 v[42:45], v[122:125], v[94:97], v[42:45]
	v_mfma_f32_16x16x32_bf16 v[46:49], v[126:129], v[94:97], v[46:49]
	v_mfma_f32_16x16x32_bf16 v[50:53], v[58:61], v[94:97], v[50:53]
	v_mfma_f32_16x16x32_bf16 v[54:57], v[62:65], v[94:97], v[54:57]
	s_cmp_eq_u32 s73, 0
	s_cbranch_scc1 .Lrg_v_B_end
	s_waitcnt vmcnt(0)
	s_barrier
	ds_read_b128 v[122:125], v219 offset:8192
	ds_read_b128 v[126:129], v219 offset:8448
	ds_read_b128 v[58:61], v219 offset:8704
	ds_read_b128 v[62:65], v219 offset:8960
	s_waitcnt lgkmcnt(4)
	v_mfma_f32_16x16x32_bf16 v[22:25], v[106:109], v[102:105], v[22:25]
	v_mfma_f32_16x16x32_bf16 v[30:33], v[110:113], v[102:105], v[30:33]
	v_mfma_f32_16x16x32_bf16 v[34:37], v[114:117], v[102:105], v[34:37]
	v_mfma_f32_16x16x32_bf16 v[38:41], v[118:121], v[102:105], v[38:41]
	s_waitcnt lgkmcnt(0)
	v_mfma_f32_16x16x32_bf16 v[42:45], v[122:125], v[102:105], v[42:45]
	v_mfma_f32_16x16x32_bf16 v[46:49], v[126:129], v[102:105], v[46:49]
	v_mfma_f32_16x16x32_bf16 v[50:53], v[58:61], v[102:105], v[50:53]
	v_mfma_f32_16x16x32_bf16 v[54:57], v[62:65], v[102:105], v[54:57]

; #define LAS __attribute__((address_space(3)))
; #define ATT_KLOAD(buf, p) do { const bf16_t* kp_ = kloc + (size_t)((p) * 8 * NH) * 1024; \
;         _Pragma("unroll") for (int f = 0; f < 2; ++f) _Pragma("unroll") for (int ks = 0; ks < 4; ++ks) ka[buf][f * 4 + ks] = *(const bf16x8*)(kp_ + f * 128 + ks * 256); } while (0)
; template <bool LOCAL>
; __device__ __forceinline__ void attn_unit(const bf16_t* Q, const bf16_t* KT, const bf16_t* VT, bf16_t* O, LAS unsigned char* lds, int b, int h, int r, int w, int tq, int lane) {
;     const int g = lane >> 4, q = lane & 15;
;     const int qrow = LOCAL ? (b * SEQ + r * GRID_W + 16 * w + q) : (ML + b * CTX + 16 * tq + q);
;     bf16x8 bq[4];
;     { const bf16_t* qp = Q + (size_t)qrow * D + h * HD + 8 * g;
; #pragma unroll
;       for (int ks = 0; ks < 4; ++ks) bq[ks] = *(const bf16x8*)(qp + 32 * ks); }
;     constexpr int NP = LOCAL ? 16 : 8, CP = LOCAL ? 8 : 0;
;     f32x4 s[2 * NP];
;     int rs = 0, ws = 0;
;     if (LOCAL) { rs = r - 4; rs = rs < 0 ? 0 : (rs > 24 ? 24 : rs); ws = 16 * w - 8; ws = ws < 0 ? 0 : (ws > 32 ? 32 : ws); }
;     const int rgl = b * SEQ + rs * GRID_W + ws;
;     if (LOCAL) {
;         const bf16_t* kloc = KT + ((size_t)(((rgl >> 3) + (q >> 2)) * NH + h)) * 1024 + (q & 3) * 32 + g * 8;
;         bf16x8 ka[2][8];
;     ...
;         ATT_KLOAD(0, 0);
; #pragma unroll
;         for (int p = 0; p < 8; ++p) {
;             __builtin_amdgcn_s_barrier();
;             if (p + 1 < 8) ATT_KLOAD((p + 1) & 1, p + 1);
;             __builtin_amdgcn_sched_barrier(0);
; #pragma unroll
;             for (int f = 0; f < 2; ++f) { f32x4 a = {0.f, 0.f, 0.f, 0.f};
; #pragma unroll
;                 for (int ks = 0; ks < 4; ++ks) a = __builtin_amdgcn_mfma_f32_16x16x32_bf16(ka[p & 1][f * 4 + ks], bq[ks], a, 0, 0, 0);
;                 s[2 * p + f] = a; }
;             __builtin_amdgcn_sched_barrier(0);
;         }
;     ...
;     }
;     {
;         const LAS unsigned char* kl = lds + (q >> 2) * 2048 + (((q & 3) * 4 + g) ^ ((q >> 2) & 2)) * 16;
; #pragma unroll
;         for (int p = 0; p < 8; ++p)
; #pragma unroll
;             for (int f = 0; f < 2; ++f) { f32x4 a = {0.f, 0.f, 0.f, 0.f};
; #pragma unroll
;                 for (int ks = 0; ks < 4; ++ks) a = __builtin_amdgcn_mfma_f32_16x16x32_bf16(*(const LAS bf16x8*)(kl + p * 8192 + ks * 512 + f * 256), bq[ks], a, 0, 0, 0);
;                 s[2 * (CP + p) + f] = a; }
.LBB9_674:
	v_ashrrev_i32_e32 v163, 31, v162
	v_lshlrev_b64 v[2:3], 12, v[162:163]
	s_mov_b32 s4, s52
	v_lshl_add_u64 v[2:3], v[158:159], 0, v[2:3]
	global_load_dwordx4 v[138:141], v[2:3], off
	global_load_dwordx4 v[134:137], v[2:3], off offset:64
	global_load_dwordx4 v[130:133], v[2:3], off offset:128
	global_load_dwordx4 v[62:65], v[2:3], off offset:192
	v_med3_i32 v2, s4, 4, 28
	v_lshlrev_b32_e32 v2, 6, v2
	v_add_u32_e32 v2, v2, v157
	v_add_u32_e32 v2, 0xffffff00, v2
	v_ashrrev_i32_e32 v194, 3, v2
	v_add_u32_e32 v2, v194, v168
	v_lshl_or_b32 v2, v2, 4, s72
	v_ashrrev_i32_e32 v3, 31, v2
	v_lshlrev_b64 v[2:3], 11, v[2:3]
	v_lshl_add_u64 v[70:71], v[146:147], 0, v[2:3]
	v_med3_i32 v232, s52, 4, 28
	v_add_u32_e32 v195, s51, v232
	s_lshr_b32 s54, s57, 2
	s_sub_i32 s54, s52, s54
	s_add_i32 s55, s54, -4
	s_max_i32 s55, s55, 0
	s_min_i32 s55, s55, 24
	s_add_i32 s73, s54, -3
	s_max_i32 s73, s73, 0
	s_min_i32 s73, s73, 24
	s_sub_i32 s73, s73, s55
	s_lshr_b32 s54, s57, 2
	s_mul_i32 s53, s73, s54
	s_ashr_i32 s54, s70, 6
	s_lshl_b32 s54, s54, 8
	s_lshl_b32 s55, s55, 3
	s_add_i32 s54, s54, s55
	s_add_i32 s54, s54, s57
	s_lshl_b32 s54, s54, 15
	s_lshl_b32 s55, s72, 11
	s_add_i32 s28, s54, s55
	s_mov_b32 s75, 0x200000
	s_lshl_b32 s54, s57, 10
	s_add_i32 s59, s54, 0x10000
	s_and_b32 s54, s57, 1
	s_lshl_b32 s54, s54, 1
	v_xor_b32_e32 v218, s54, v164
	v_lshlrev_b32_e32 v218, 4, v218
	v_add_u32_e32 v218, s28, v218
	ds_read_b64 v[220:221], v241 offset:192
	s_waitcnt lgkmcnt(0)
	v_add_co_u32_e32 v220, vcc, 0x21f00000, v220
	s_nop 1
	v_addc_co_u32_e32 v221, vcc, 0, v221, vcc
	v_add_co_u32_e32 v220, vcc, v220, v218
	s_nop 1
	v_addc_co_u32_e32 v221, vcc, 0, v221, vcc
	v_add_co_u32_e32 v226, vcc, 0x400, v220
	s_nop 1
	v_addc_co_u32_e32 v227, vcc, 0, v221, vcc
	s_and_b32 s55, s57, 3
	s_lshl_b32 s55, s55, 1
	s_add_i32 s55, s55, -1
	s_max_i32 s55, s55, 0
	s_min_i32 s55, s55, 4
	v_lshrrev_b32_e32 v219, 2, v166
	v_add_u32_e32 v219, s55, v219
	v_and_b32_e32 v224, 3, v166
	v_lshl_or_b32 v224, v224, 2, v165
	v_and_b32_e32 v225, 1, v219
	v_lshlrev_b32_e32 v225, 1, v225
	v_xor_b32_e32 v224, v224, v225
	v_lshlrev_b32_e32 v224, 4, v224
	v_lshl_add_u32 v219, v219, 10, v224
	v_add_u32_e32 v219, 0x10000, v219
	s_add_i32 m0, s59, 0
	s_nop 0
	global_load_lds_dwordx4 v[220:221], off
	s_add_i32 m0, s59, 8192
	s_nop 0
	global_load_lds_dwordx4 v[226:227], off
	s_add_i32 m0, s59, 16384
	v_add_co_u32_e32 v222, vcc, s6, v220
	s_nop 1
	v_addc_co_u32_e32 v223, vcc, 0, v221, vcc
	global_load_lds_dwordx4 v[222:223], off
	s_add_i32 m0, s59, 24576
	v_add_co_u32_e32 v222, vcc, s6, v226
	s_nop 1
	v_addc_co_u32_e32 v223, vcc, 0, v227, vcc
	global_load_lds_dwordx4 v[222:223], off
	s_add_i32 m0, s59, 32768
	v_add_co_u32_e32 v222, vcc, s7, v220
	s_nop 1
	v_addc_co_u32_e32 v223, vcc, 0, v221, vcc
	global_load_lds_dwordx4 v[222:223], off
	s_add_i32 m0, s59, 40960
	v_add_co_u32_e32 v222, vcc, s7, v226
	s_nop 1
	v_addc_co_u32_e32 v223, vcc, 0, v227, vcc
	global_load_lds_dwordx4 v[222:223], off
	s_add_i32 m0, s59, 49152
	v_add_co_u32_e32 v222, vcc, s2, v220
	s_nop 1
	v_addc_co_u32_e32 v223, vcc, 0, v221, vcc
	global_load_lds_dwordx4 v[222:223], off
	s_cmp_eq_u32 s53, 0
	s_cbranch_scc0 .Lrg_k_B
	s_waitcnt vmcnt(6)
	s_barrier
	ds_read_b128 v[2:5], v219 offset:0
	ds_read_b128 v[6:9], v219 offset:256
	ds_read_b128 v[10:13], v219 offset:512
	ds_read_b128 v[14:17], v219 offset:768
	s_waitcnt vmcnt(5)
	s_barrier
	s_add_i32 m0, s59, 57344
	v_add_co_u32_e32 v222, vcc, s2, v226
	s_nop 1
	v_addc_co_u32_e32 v223, vcc, 0, v227, vcc
	global_load_lds_dwordx4 v[222:223], off
	ds_read_b128 v[18:21], v219 offset:8192
	ds_read_b128 v[22:25], v219 offset:8448
	ds_read_b128 v[26:29], v219 offset:8704
	ds_read_b128 v[30:33], v219 offset:8960
	s_waitcnt lgkmcnt(4)
	v_mfma_f32_16x16x32_bf16 v[126:129], v[2:5], v[138:141], 0
	v_mfma_f32_16x16x32_bf16 v[122:125], v[6:9], v[138:141], 0
	v_mfma_f32_16x16x32_bf16 v[126:129], v[10:13], v[134:137], v[126:129]
	v_mfma_f32_16x16x32_bf16 v[122:125], v[14:17], v[134:137], v[122:125]
	s_waitcnt vmcnt(5)
	s_barrier
	s_add_i32 m0, s59, 0
	v_add_co_u32_e32 v222, vcc, s60, v220
	s_nop 1
	v_addc_co_u32_e32 v223, vcc, 0, v221, vcc
	global_load_lds_dwordx4 v[222:223], off
	ds_read_b128 v[2:5], v219 offset:16384
	ds_read_b128 v[6:9], v219 offset:16640
	ds_read_b128 v[10:13], v219 offset:16896
	ds_read_b128 v[14:17], v219 offset:17152
	s_waitcnt lgkmcnt(4)
	v_mfma_f32_16x16x32_bf16 v[126:129], v[18:21], v[130:133], v[126:129]
	v_mfma_f32_16x16x32_bf16 v[122:125], v[22:25], v[130:133], v[122:125]
	v_mfma_f32_16x16x32_bf16 v[126:129], v[26:29], v[62:65], v[126:129]
	v_mfma_f32_16x16x32_bf16 v[122:125], v[30:33], v[62:65], v[122:125]
	s_waitcnt vmcnt(5)
	s_barrier
	s_add_i32 m0, s59, 8192
	v_add_co_u32_e32 v222, vcc, s60, v226
	s_nop 1
	v_addc_co_u32_e32 v223, vcc, 0, v227, vcc
	global_load_lds_dwordx4 v[222:223], off
	ds_read_b128 v[18:21], v219 offset:24576
	ds_read_b128 v[22:25], v219 offset:24832
	ds_read_b128 v[26:29], v219 offset:25088
	ds_read_b128 v[30:33], v219 offset:25344
	s_waitcnt lgkmcnt(4)
	v_mfma_f32_16x16x32_bf16 v[118:121], v[2:5], v[138:141], 0
	v_mfma_f32_16x16x32_bf16 v[114:117], v[6:9], v[138:141], 0
	v_mfma_f32_16x16x32_bf16 v[118:121], v[10:13], v[134:137], v[118:121]
	v_mfma_f32_16x16x32_bf16 v[114:117], v[14:17], v[134:137], v[114:117]
	s_waitcnt vmcnt(5)
	s_barrier
; #define LAS __attribute__((address_space(3)))
; #define ATT_KLOAD(buf, p) do { const bf16_t* kp_ = kloc + (size_t)((p) * 8 * NH) * 1024; \
;         _Pragma("unroll") for (int f = 0; f < 2; ++f) _Pragma("unroll") for (int ks = 0; ks < 4; ++ks) ka[buf][f * 4 + ks] = *(const bf16x8*)(kp_ + f * 128 + ks * 256); } while (0)
; template <bool LOCAL>
; __device__ __forceinline__ void attn_unit(const bf16_t* Q, const bf16_t* KT, const bf16_t* VT, bf16_t* O, LAS unsigned char* lds, int b, int h, int r, int w, int tq, int lane) {
;     ...
;     if (LOCAL) {
;         const bf16_t* kloc = KT + ((size_t)(((rgl >> 3) + (q >> 2)) * NH + h)) * 1024 + (q & 3) * 32 + g * 8;
;         bf16x8 ka[2][8];
;     ...
;         ATT_KLOAD(0, 0);
; #pragma unroll
;         for (int p = 0; p < 8; ++p) {
;             __builtin_amdgcn_s_barrier();
;             if (p + 1 < 8) ATT_KLOAD((p + 1) & 1, p + 1);
;             __builtin_amdgcn_sched_barrier(0);
; #pragma unroll
;             for (int f = 0; f < 2; ++f) { f32x4 a = {0.f, 0.f, 0.f, 0.f};
; #pragma unroll
;                 for (int ks = 0; ks < 4; ++ks) a = __builtin_amdgcn_mfma_f32_16x16x32_bf16(ka[p & 1][f * 4 + ks], bq[ks], a, 0, 0, 0);
;                 s[2 * p + f] = a; }
;             __builtin_amdgcn_sched_barrier(0);
;         }
;     ...
;     }
;     {
;         const LAS unsigned char* kl = lds + (q >> 2) * 2048 + (((q & 3) * 4 + g) ^ ((q >> 2) & 2)) * 16;
; #pragma unroll
;         for (int p = 0; p < 8; ++p)
; #pragma unroll
;             for (int f = 0; f < 2; ++f) { f32x4 a = {0.f, 0.f, 0.f, 0.f};
; #pragma unroll
;                 for (int ks = 0; ks < 4; ++ks) a = __builtin_amdgcn_mfma_f32_16x16x32_bf16(*(const LAS bf16x8*)(kl + p * 8192 + ks * 512 + f * 256), bq[ks], a, 0, 0, 0);
;                 s[2 * (CP + p) + f] = a; }
	s_add_i32 m0, s59, 16384
	v_add_co_u32_e32 v222, vcc, s61, v220
	s_nop 1
	v_addc_co_u32_e32 v223, vcc, 0, v221, vcc
	global_load_lds_dwordx4 v[222:223], off
	ds_read_b128 v[2:5], v219 offset:32768
	ds_read_b128 v[6:9], v219 offset:33024
	ds_read_b128 v[10:13], v219 offset:33280
	ds_read_b128 v[14:17], v219 offset:33536
	s_waitcnt lgkmcnt(4)
	v_mfma_f32_16x16x32_bf16 v[118:121], v[18:21], v[130:133], v[118:121]
	v_mfma_f32_16x16x32_bf16 v[114:117], v[22:25], v[130:133], v[114:117]
	v_mfma_f32_16x16x32_bf16 v[118:121], v[26:29], v[62:65], v[118:121]
	v_mfma_f32_16x16x32_bf16 v[114:117], v[30:33], v[62:65], v[114:117]
	s_waitcnt vmcnt(5)
	s_barrier
	s_add_i32 m0, s59, 24576
	v_add_co_u32_e32 v222, vcc, s61, v226
	s_nop 1
	v_addc_co_u32_e32 v223, vcc, 0, v227, vcc
	global_load_lds_dwordx4 v[222:223], off
	ds_read_b128 v[18:21], v219 offset:40960
	ds_read_b128 v[22:25], v219 offset:41216
	ds_read_b128 v[26:29], v219 offset:41472
	ds_read_b128 v[30:33], v219 offset:41728
	s_waitcnt lgkmcnt(4)
	v_mfma_f32_16x16x32_bf16 v[110:113], v[2:5], v[138:141], 0
	v_mfma_f32_16x16x32_bf16 v[106:109], v[6:9], v[138:141], 0
	v_mfma_f32_16x16x32_bf16 v[110:113], v[10:13], v[134:137], v[110:113]
	v_mfma_f32_16x16x32_bf16 v[106:109], v[14:17], v[134:137], v[106:109]
	s_waitcnt vmcnt(5)
	s_barrier
	s_add_i32 m0, s59, 32768
	v_add_co_u32_e32 v222, vcc, s17, v220
	s_nop 1
	v_addc_co_u32_e32 v223, vcc, 0, v221, vcc
	global_load_lds_dwordx4 v[222:223], off
	ds_read_b128 v[2:5], v219 offset:49152
	ds_read_b128 v[6:9], v219 offset:49408
	ds_read_b128 v[10:13], v219 offset:49664
	ds_read_b128 v[14:17], v219 offset:49920
	s_waitcnt lgkmcnt(4)
	v_mfma_f32_16x16x32_bf16 v[110:113], v[18:21], v[130:133], v[110:113]
	v_mfma_f32_16x16x32_bf16 v[106:109], v[22:25], v[130:133], v[106:109]
	v_mfma_f32_16x16x32_bf16 v[110:113], v[26:29], v[62:65], v[110:113]
	v_mfma_f32_16x16x32_bf16 v[106:109], v[30:33], v[62:65], v[106:109]
	s_waitcnt vmcnt(5)
	s_barrier
	s_add_i32 m0, s59, 40960
	v_add_co_u32_e32 v222, vcc, s17, v226
	s_nop 1
	v_addc_co_u32_e32 v223, vcc, 0, v227, vcc
	global_load_lds_dwordx4 v[222:223], off
	ds_read_b128 v[18:21], v219 offset:57344
	ds_read_b128 v[22:25], v219 offset:57600
	ds_read_b128 v[26:29], v219 offset:57856
	ds_read_b128 v[30:33], v219 offset:58112
	s_waitcnt lgkmcnt(4)
	v_mfma_f32_16x16x32_bf16 v[102:105], v[2:5], v[138:141], 0
	v_mfma_f32_16x16x32_bf16 v[98:101], v[6:9], v[138:141], 0
	v_mfma_f32_16x16x32_bf16 v[102:105], v[10:13], v[134:137], v[102:105]
	v_mfma_f32_16x16x32_bf16 v[98:101], v[14:17], v[134:137], v[98:101]
	s_waitcnt vmcnt(5)
	s_barrier
	s_add_i32 m0, s59, 49152
	v_add_co_u32_e32 v222, vcc, s62, v220
	s_nop 1
	v_addc_co_u32_e32 v223, vcc, 0, v221, vcc
	global_load_lds_dwordx4 v[222:223], off
	ds_read_b128 v[2:5], v219 offset:0
	ds_read_b128 v[6:9], v219 offset:256
	ds_read_b128 v[10:13], v219 offset:512
	ds_read_b128 v[14:17], v219 offset:768
	s_waitcnt lgkmcnt(4)
	v_mfma_f32_16x16x32_bf16 v[102:105], v[18:21], v[130:133], v[102:105]
	v_mfma_f32_16x16x32_bf16 v[98:101], v[22:25], v[130:133], v[98:101]
	v_mfma_f32_16x16x32_bf16 v[102:105], v[26:29], v[62:65], v[102:105]
	v_mfma_f32_16x16x32_bf16 v[98:101], v[30:33], v[62:65], v[98:101]
	s_waitcnt vmcnt(5)
	s_barrier
	s_add_i32 m0, s59, 57344
	v_add_co_u32_e32 v222, vcc, s62, v226
	s_nop 1
	v_addc_co_u32_e32 v223, vcc, 0, v227, vcc
	global_load_lds_dwordx4 v[222:223], off
	ds_read_b128 v[18:21], v219 offset:8192
	ds_read_b128 v[22:25], v219 offset:8448
	ds_read_b128 v[26:29], v219 offset:8704
	ds_read_b128 v[30:33], v219 offset:8960
	s_waitcnt lgkmcnt(4)
	v_mfma_f32_16x16x32_bf16 v[94:97], v[2:5], v[138:141], 0
	v_mfma_f32_16x16x32_bf16 v[90:93], v[6:9], v[138:141], 0
	v_mfma_f32_16x16x32_bf16 v[94:97], v[10:13], v[134:137], v[94:97]
	v_mfma_f32_16x16x32_bf16 v[90:93], v[14:17], v[134:137], v[90:93]
	s_waitcnt vmcnt(5)
	s_barrier
	s_cmp_eq_u32 s73, 0
	s_cbranch_scc1 .Lrg_k_A_nd9
	s_add_i32 m0, s59, 0
	v_add_co_u32_e32 v222, vcc, s75, v220
	s_nop 1
	v_addc_co_u32_e32 v223, vcc, 0, v221, vcc
	global_load_lds_dwordx4 v[222:223], off
; #define LAS __attribute__((address_space(3)))
; #define ATT_KLOAD(buf, p) do { const bf16_t* kp_ = kloc + (size_t)((p) * 8 * NH) * 1024; \
;         _Pragma("unroll") for (int f = 0; f < 2; ++f) _Pragma("unroll") for (int ks = 0; ks < 4; ++ks) ka[buf][f * 4 + ks] = *(const bf16x8*)(kp_ + f * 128 + ks * 256); } while (0)
; template <bool LOCAL>
; __device__ __forceinline__ void attn_unit(const bf16_t* Q, const bf16_t* KT, const bf16_t* VT, bf16_t* O, LAS unsigned char* lds, int b, int h, int r, int w, int tq, int lane) {
;     ...
;     if (LOCAL) {
;         const bf16_t* kloc = KT + ((size_t)(((rgl >> 3) + (q >> 2)) * NH + h)) * 1024 + (q & 3) * 32 + g * 8;
;         bf16x8 ka[2][8];
;     ...
;         ATT_KLOAD(0, 0);
; #pragma unroll
;         for (int p = 0; p < 8; ++p) {
;             __builtin_amdgcn_s_barrier();
;             if (p + 1 < 8) ATT_KLOAD((p + 1) & 1, p + 1);
;             __builtin_amdgcn_sched_barrier(0);
; #pragma unroll
;             for (int f = 0; f < 2; ++f) { f32x4 a = {0.f, 0.f, 0.f, 0.f};
; #pragma unroll
;                 for (int ks = 0; ks < 4; ++ks) a = __builtin_amdgcn_mfma_f32_16x16x32_bf16(ka[p & 1][f * 4 + ks], bq[ks], a, 0, 0, 0);
;                 s[2 * p + f] = a; }
;             __builtin_amdgcn_sched_barrier(0);
;         }
;     ...
;     }
;     {
;         const LAS unsigned char* kl = lds + (q >> 2) * 2048 + (((q & 3) * 4 + g) ^ ((q >> 2) & 2)) * 16;
; #pragma unroll
;         for (int p = 0; p < 8; ++p)
; #pragma unroll
;             for (int f = 0; f < 2; ++f) { f32x4 a = {0.f, 0.f, 0.f, 0.f};
; #pragma unroll
;                 for (int ks = 0; ks < 4; ++ks) a = __builtin_amdgcn_mfma_f32_16x16x32_bf16(*(const LAS bf16x8*)(kl + p * 8192 + ks * 512 + f * 256), bq[ks], a, 0, 0, 0);
;                 s[2 * (CP + p) + f] = a; }
.Lrg_k_A_nd9:
	ds_read_b128 v[2:5], v219 offset:16384
	ds_read_b128 v[6:9], v219 offset:16640
	ds_read_b128 v[10:13], v219 offset:16896
	ds_read_b128 v[14:17], v219 offset:17152
	s_waitcnt lgkmcnt(4)
	v_mfma_f32_16x16x32_bf16 v[94:97], v[18:21], v[130:133], v[94:97]
	v_mfma_f32_16x16x32_bf16 v[90:93], v[22:25], v[130:133], v[90:93]
	v_mfma_f32_16x16x32_bf16 v[94:97], v[26:29], v[62:65], v[94:97]
	v_mfma_f32_16x16x32_bf16 v[90:93], v[30:33], v[62:65], v[90:93]
	s_waitcnt vmcnt(4)
	s_barrier
	s_cmp_eq_u32 s73, 0
	s_cbranch_scc1 .Lrg_k_A_nd10
	s_add_i32 m0, s59, 8192
	v_add_co_u32_e32 v222, vcc, s75, v226
	s_nop 1
	v_addc_co_u32_e32 v223, vcc, 0, v227, vcc
	global_load_lds_dwordx4 v[222:223], off
.Lrg_k_A_nd10:
	ds_read_b128 v[18:21], v219 offset:24576
	ds_read_b128 v[22:25], v219 offset:24832
	ds_read_b128 v[26:29], v219 offset:25088
	ds_read_b128 v[30:33], v219 offset:25344
	s_waitcnt lgkmcnt(4)
	v_mfma_f32_16x16x32_bf16 v[86:89], v[2:5], v[138:141], 0
	v_mfma_f32_16x16x32_bf16 v[82:85], v[6:9], v[138:141], 0
	v_mfma_f32_16x16x32_bf16 v[86:89], v[10:13], v[134:137], v[86:89]
	v_mfma_f32_16x16x32_bf16 v[82:85], v[14:17], v[134:137], v[82:85]
	s_waitcnt vmcnt(3)
	s_barrier
	ds_read_b128 v[2:5], v219 offset:32768
	ds_read_b128 v[6:9], v219 offset:33024
	ds_read_b128 v[10:13], v219 offset:33280
	ds_read_b128 v[14:17], v219 offset:33536
	s_waitcnt lgkmcnt(4)
	v_mfma_f32_16x16x32_bf16 v[86:89], v[18:21], v[130:133], v[86:89]
	v_mfma_f32_16x16x32_bf16 v[82:85], v[22:25], v[130:133], v[82:85]
	v_mfma_f32_16x16x32_bf16 v[86:89], v[26:29], v[62:65], v[86:89]
	v_mfma_f32_16x16x32_bf16 v[82:85], v[30:33], v[62:65], v[82:85]
	s_waitcnt vmcnt(2)
	s_barrier
	ds_read_b128 v[18:21], v219 offset:40960
	ds_read_b128 v[22:25], v219 offset:41216
	ds_read_b128 v[26:29], v219 offset:41472
	ds_read_b128 v[30:33], v219 offset:41728
	s_waitcnt lgkmcnt(4)
	v_mfma_f32_16x16x32_bf16 v[78:81], v[2:5], v[138:141], 0
	v_mfma_f32_16x16x32_bf16 v[74:77], v[6:9], v[138:141], 0
	v_mfma_f32_16x16x32_bf16 v[78:81], v[10:13], v[134:137], v[78:81]
	v_mfma_f32_16x16x32_bf16 v[74:77], v[14:17], v[134:137], v[74:77]
	s_waitcnt vmcnt(1)
	s_barrier
	ds_read_b128 v[2:5], v219 offset:49152
	ds_read_b128 v[6:9], v219 offset:49408
	ds_read_b128 v[10:13], v219 offset:49664
	ds_read_b128 v[14:17], v219 offset:49920
	s_waitcnt lgkmcnt(4)
	v_mfma_f32_16x16x32_bf16 v[78:81], v[18:21], v[130:133], v[78:81]
	v_mfma_f32_16x16x32_bf16 v[74:77], v[22:25], v[130:133], v[74:77]
	v_mfma_f32_16x16x32_bf16 v[78:81], v[26:29], v[62:65], v[78:81]
	v_mfma_f32_16x16x32_bf16 v[74:77], v[30:33], v[62:65], v[74:77]
	s_waitcnt vmcnt(0)
	s_barrier
	ds_read_b128 v[18:21], v219 offset:57344
	ds_read_b128 v[22:25], v219 offset:57600
	ds_read_b128 v[26:29], v219 offset:57856
	ds_read_b128 v[30:33], v219 offset:58112
	s_waitcnt lgkmcnt(4)
	v_mfma_f32_16x16x32_bf16 v[70:73], v[2:5], v[138:141], 0
	v_mfma_f32_16x16x32_bf16 v[66:69], v[6:9], v[138:141], 0
	v_mfma_f32_16x16x32_bf16 v[70:73], v[10:13], v[134:137], v[70:73]
	v_mfma_f32_16x16x32_bf16 v[66:69], v[14:17], v[134:137], v[66:69]
	s_waitcnt vmcnt(1)
	s_barrier
	s_waitcnt lgkmcnt(0)
	v_mfma_f32_16x16x32_bf16 v[70:73], v[18:21], v[130:133], v[70:73]
	v_mfma_f32_16x16x32_bf16 v[66:69], v[22:25], v[130:133], v[66:69]
	v_mfma_f32_16x16x32_bf16 v[70:73], v[26:29], v[62:65], v[70:73]
	v_mfma_f32_16x16x32_bf16 v[66:69], v[30:33], v[62:65], v[66:69]
	s_cmp_eq_u32 s73, 0
	s_cbranch_scc1 .Lrg_k_A_end
	s_waitcnt vmcnt(0)
	s_barrier

; #define LAS __attribute__((address_space(3)))
; #define ATT_KLOAD(buf, p) do { const bf16_t* kp_ = kloc + (size_t)((p) * 8 * NH) * 1024; \
;         _Pragma("unroll") for (int f = 0; f < 2; ++f) _Pragma("unroll") for (int ks = 0; ks < 4; ++ks) ka[buf][f * 4 + ks] = *(const bf16x8*)(kp_ + f * 128 + ks * 256); } while (0)
; template <bool LOCAL>
; __device__ __forceinline__ void attn_unit(const bf16_t* Q, const bf16_t* KT, const bf16_t* VT, bf16_t* O, LAS unsigned char* lds, int b, int h, int r, int w, int tq, int lane) {
;     ...
;     if (LOCAL) {
;         const bf16_t* kloc = KT + ((size_t)(((rgl >> 3) + (q >> 2)) * NH + h)) * 1024 + (q & 3) * 32 + g * 8;
;         bf16x8 ka[2][8];
;     ...
;         ATT_KLOAD(0, 0);
; #pragma unroll
;         for (int p = 0; p < 8; ++p) {
;             __builtin_amdgcn_s_barrier();
;             if (p + 1 < 8) ATT_KLOAD((p + 1) & 1, p + 1);
;             __builtin_amdgcn_sched_barrier(0);
; #pragma unroll
;             for (int f = 0; f < 2; ++f) { f32x4 a = {0.f, 0.f, 0.f, 0.f};
; #pragma unroll
;                 for (int ks = 0; ks < 4; ++ks) a = __builtin_amdgcn_mfma_f32_16x16x32_bf16(ka[p & 1][f * 4 + ks], bq[ks], a, 0, 0, 0);
;                 s[2 * p + f] = a; }
;             __builtin_amdgcn_sched_barrier(0);
;         }
;     ...
;     }
;     {
;         const LAS unsigned char* kl = lds + (q >> 2) * 2048 + (((q & 3) * 4 + g) ^ ((q >> 2) & 2)) * 16;
; #pragma unroll
;         for (int p = 0; p < 8; ++p)
; #pragma unroll
;             for (int f = 0; f < 2; ++f) { f32x4 a = {0.f, 0.f, 0.f, 0.f};
; #pragma unroll
;                 for (int ks = 0; ks < 4; ++ks) a = __builtin_amdgcn_mfma_f32_16x16x32_bf16(*(const LAS bf16x8*)(kl + p * 8192 + ks * 512 + f * 256), bq[ks], a, 0, 0, 0);
;                 s[2 * (CP + p) + f] = a; }
.Lrg_k_B:
	s_waitcnt vmcnt(6)
	s_barrier
	s_waitcnt vmcnt(5)
	s_barrier
	s_add_i32 m0, s59, 57344
	v_add_co_u32_e32 v222, vcc, s2, v226
	s_nop 1
	v_addc_co_u32_e32 v223, vcc, 0, v227, vcc
	global_load_lds_dwordx4 v[222:223], off
	s_waitcnt vmcnt(5)
	s_barrier
	s_add_i32 m0, s59, 0
	v_add_co_u32_e32 v222, vcc, s60, v220
	s_nop 1
	v_addc_co_u32_e32 v223, vcc, 0, v221, vcc
	global_load_lds_dwordx4 v[222:223], off
	ds_read_b128 v[2:5], v219 offset:16384
	ds_read_b128 v[6:9], v219 offset:16640
	ds_read_b128 v[10:13], v219 offset:16896
	ds_read_b128 v[14:17], v219 offset:17152
	s_waitcnt vmcnt(5)
	s_barrier
	s_add_i32 m0, s59, 8192
	v_add_co_u32_e32 v222, vcc, s60, v226
	s_nop 1
	v_addc_co_u32_e32 v223, vcc, 0, v227, vcc
	global_load_lds_dwordx4 v[222:223], off
	ds_read_b128 v[18:21], v219 offset:24576
	ds_read_b128 v[22:25], v219 offset:24832
	ds_read_b128 v[26:29], v219 offset:25088
	ds_read_b128 v[30:33], v219 offset:25344
	s_waitcnt lgkmcnt(4)
	v_mfma_f32_16x16x32_bf16 v[126:129], v[2:5], v[138:141], 0
	v_mfma_f32_16x16x32_bf16 v[122:125], v[6:9], v[138:141], 0
	v_mfma_f32_16x16x32_bf16 v[126:129], v[10:13], v[134:137], v[126:129]
	v_mfma_f32_16x16x32_bf16 v[122:125], v[14:17], v[134:137], v[122:125]
	s_waitcnt vmcnt(5)
	s_barrier
	s_add_i32 m0, s59, 16384
	v_add_co_u32_e32 v222, vcc, s61, v220
	s_nop 1
	v_addc_co_u32_e32 v223, vcc, 0, v221, vcc
	global_load_lds_dwordx4 v[222:223], off
	ds_read_b128 v[2:5], v219 offset:32768
	ds_read_b128 v[6:9], v219 offset:33024
	ds_read_b128 v[10:13], v219 offset:33280
	ds_read_b128 v[14:17], v219 offset:33536
	s_waitcnt lgkmcnt(4)
	v_mfma_f32_16x16x32_bf16 v[126:129], v[18:21], v[130:133], v[126:129]
	v_mfma_f32_16x16x32_bf16 v[122:125], v[22:25], v[130:133], v[122:125]
	v_mfma_f32_16x16x32_bf16 v[126:129], v[26:29], v[62:65], v[126:129]
	v_mfma_f32_16x16x32_bf16 v[122:125], v[30:33], v[62:65], v[122:125]
	s_waitcnt vmcnt(5)
	s_barrier
	s_add_i32 m0, s59, 24576
	v_add_co_u32_e32 v222, vcc, s61, v226
	s_nop 1
	v_addc_co_u32_e32 v223, vcc, 0, v227, vcc
	global_load_lds_dwordx4 v[222:223], off
	ds_read_b128 v[18:21], v219 offset:40960
	ds_read_b128 v[22:25], v219 offset:41216
	ds_read_b128 v[26:29], v219 offset:41472
	ds_read_b128 v[30:33], v219 offset:41728
	s_waitcnt lgkmcnt(4)
	v_mfma_f32_16x16x32_bf16 v[118:121], v[2:5], v[138:141], 0
	v_mfma_f32_16x16x32_bf16 v[114:117], v[6:9], v[138:141], 0
	v_mfma_f32_16x16x32_bf16 v[118:121], v[10:13], v[134:137], v[118:121]
	v_mfma_f32_16x16x32_bf16 v[114:117], v[14:17], v[134:137], v[114:117]
	s_waitcnt vmcnt(5)
	s_barrier
	s_add_i32 m0, s59, 32768
	v_add_co_u32_e32 v222, vcc, s17, v220
	s_nop 1
	v_addc_co_u32_e32 v223, vcc, 0, v221, vcc
	global_load_lds_dwordx4 v[222:223], off
	ds_read_b128 v[2:5], v219 offset:49152
	ds_read_b128 v[6:9], v219 offset:49408
	ds_read_b128 v[10:13], v219 offset:49664
	ds_read_b128 v[14:17], v219 offset:49920
	s_waitcnt lgkmcnt(4)
	v_mfma_f32_16x16x32_bf16 v[118:121], v[18:21], v[130:133], v[118:121]
	v_mfma_f32_16x16x32_bf16 v[114:117], v[22:25], v[130:133], v[114:117]
	v_mfma_f32_16x16x32_bf16 v[118:121], v[26:29], v[62:65], v[118:121]
	v_mfma_f32_16x16x32_bf16 v[114:117], v[30:33], v[62:65], v[114:117]
	s_waitcnt vmcnt(5)
	s_barrier
	s_add_i32 m0, s59, 40960
	v_add_co_u32_e32 v222, vcc, s17, v226
	s_nop 1
	v_addc_co_u32_e32 v223, vcc, 0, v227, vcc
	global_load_lds_dwordx4 v[222:223], off
	ds_read_b128 v[18:21], v219 offset:57344
	ds_read_b128 v[22:25], v219 offset:57600
	ds_read_b128 v[26:29], v219 offset:57856
	ds_read_b128 v[30:33], v219 offset:58112
	s_waitcnt lgkmcnt(4)
	v_mfma_f32_16x16x32_bf16 v[110:113], v[2:5], v[138:141], 0
	v_mfma_f32_16x16x32_bf16 v[106:109], v[6:9], v[138:141], 0
	v_mfma_f32_16x16x32_bf16 v[110:113], v[10:13], v[134:137], v[110:113]
	v_mfma_f32_16x16x32_bf16 v[106:109], v[14:17], v[134:137], v[106:109]
	s_waitcnt vmcnt(5)
	s_barrier
	s_add_i32 m0, s59, 49152
	v_add_co_u32_e32 v222, vcc, s62, v220
	s_nop 1
	v_addc_co_u32_e32 v223, vcc, 0, v221, vcc
	global_load_lds_dwordx4 v[222:223], off
	ds_read_b128 v[2:5], v219 offset:0
	ds_read_b128 v[6:9], v219 offset:256
	ds_read_b128 v[10:13], v219 offset:512
	ds_read_b128 v[14:17], v219 offset:768
	s_waitcnt lgkmcnt(4)
	v_mfma_f32_16x16x32_bf16 v[110:113], v[18:21], v[130:133], v[110:113]
	v_mfma_f32_16x16x32_bf16 v[106:109], v[22:25], v[130:133], v[106:109]
	v_mfma_f32_16x16x32_bf16 v[110:113], v[26:29], v[62:65], v[110:113]
	v_mfma_f32_16x16x32_bf16 v[106:109], v[30:33], v[62:65], v[106:109]
	s_waitcnt vmcnt(5)
	s_barrier
	s_add_i32 m0, s59, 57344
	v_add_co_u32_e32 v222, vcc, s62, v226
	s_nop 1
	v_addc_co_u32_e32 v223, vcc, 0, v227, vcc
	global_load_lds_dwordx4 v[222:223], off
	ds_read_b128 v[18:21], v219 offset:8192
	ds_read_b128 v[22:25], v219 offset:8448
	ds_read_b128 v[26:29], v219 offset:8704
	ds_read_b128 v[30:33], v219 offset:8960
	s_waitcnt lgkmcnt(4)
	v_mfma_f32_16x16x32_bf16 v[102:105], v[2:5], v[138:141], 0
	v_mfma_f32_16x16x32_bf16 v[98:101], v[6:9], v[138:141], 0
	v_mfma_f32_16x16x32_bf16 v[102:105], v[10:13], v[134:137], v[102:105]
	v_mfma_f32_16x16x32_bf16 v[98:101], v[14:17], v[134:137], v[98:101]
	s_waitcnt vmcnt(5)
	s_barrier
	s_cmp_eq_u32 s73, 0
	s_cbranch_scc1 .Lrg_k_B_nd9
	s_add_i32 m0, s59, 0
	v_add_co_u32_e32 v222, vcc, s75, v220
	s_nop 1
	v_addc_co_u32_e32 v223, vcc, 0, v221, vcc
	global_load_lds_dwordx4 v[222:223], off
; #define ATT_KLOAD(buf, p) do { const bf16_t* kp_ = kloc + (size_t)((p) * 8 * NH) * 1024; \
;         _Pragma("unroll") for (int f = 0; f < 2; ++f) _Pragma("unroll") for (int ks = 0; ks < 4; ++ks) ka[buf][f * 4 + ks] = *(const bf16x8*)(kp_ + f * 128 + ks * 256); } while (0)
; template <bool LOCAL>
; __device__ __forceinline__ void attn_unit(const bf16_t* Q, const bf16_t* KT, const bf16_t* VT, bf16_t* O, LAS unsigned char* lds, int b, int h, int r, int w, int tq, int lane) {
;     ...
;     if (LOCAL) {
;         const bf16_t* kloc = KT + ((size_t)(((rgl >> 3) + (q >> 2)) * NH + h)) * 1024 + (q & 3) * 32 + g * 8;
;         bf16x8 ka[2][8];
;     ...
;         ATT_KLOAD(0, 0);
; #pragma unroll
;         for (int p = 0; p < 8; ++p) {
;             __builtin_amdgcn_s_barrier();
;             if (p + 1 < 8) ATT_KLOAD((p + 1) & 1, p + 1);
;             __builtin_amdgcn_sched_barrier(0);
; #pragma unroll
;             for (int f = 0; f < 2; ++f) { f32x4 a = {0.f, 0.f, 0.f, 0.f};
; #pragma unroll
;                 for (int ks = 0; ks < 4; ++ks) a = __builtin_amdgcn_mfma_f32_16x16x32_bf16(ka[p & 1][f * 4 + ks], bq[ks], a, 0, 0, 0);
;                 s[2 * p + f] = a; }
;             __builtin_amdgcn_sched_barrier(0);
;         }
.Lrg_k_B_nd9:
	ds_read_b128 v[2:5], v219 offset:16384
	ds_read_b128 v[6:9], v219 offset:16640
	ds_read_b128 v[10:13], v219 offset:16896
	ds_read_b128 v[14:17], v219 offset:17152
	s_waitcnt lgkmcnt(4)
	v_mfma_f32_16x16x32_bf16 v[102:105], v[18:21], v[130:133], v[102:105]
	v_mfma_f32_16x16x32_bf16 v[98:101], v[22:25], v[130:133], v[98:101]
	v_mfma_f32_16x16x32_bf16 v[102:105], v[26:29], v[62:65], v[102:105]
	v_mfma_f32_16x16x32_bf16 v[98:101], v[30:33], v[62:65], v[98:101]
	s_waitcnt vmcnt(4)
	s_barrier
	s_cmp_eq_u32 s73, 0
	s_cbranch_scc1 .Lrg_k_B_nd10
	s_add_i32 m0, s59, 8192
	v_add_co_u32_e32 v222, vcc, s75, v226
	s_nop 1
	v_addc_co_u32_e32 v223, vcc, 0, v227, vcc
	global_load_lds_dwordx4 v[222:223], off
.Lrg_k_B_nd10:
	ds_read_b128 v[18:21], v219 offset:24576
	ds_read_b128 v[22:25], v219 offset:24832
	ds_read_b128 v[26:29], v219 offset:25088
	ds_read_b128 v[30:33], v219 offset:25344
	s_waitcnt lgkmcnt(4)
	v_mfma_f32_16x16x32_bf16 v[94:97], v[2:5], v[138:141], 0
	v_mfma_f32_16x16x32_bf16 v[90:93], v[6:9], v[138:141], 0
	v_mfma_f32_16x16x32_bf16 v[94:97], v[10:13], v[134:137], v[94:97]
	v_mfma_f32_16x16x32_bf16 v[90:93], v[14:17], v[134:137], v[90:93]
	s_waitcnt vmcnt(3)
	s_barrier
	ds_read_b128 v[2:5], v219 offset:32768
	ds_read_b128 v[6:9], v219 offset:33024
	ds_read_b128 v[10:13], v219 offset:33280
	ds_read_b128 v[14:17], v219 offset:33536
	s_waitcnt lgkmcnt(4)
	v_mfma_f32_16x16x32_bf16 v[94:97], v[18:21], v[130:133], v[94:97]
	v_mfma_f32_16x16x32_bf16 v[90:93], v[22:25], v[130:133], v[90:93]
	v_mfma_f32_16x16x32_bf16 v[94:97], v[26:29], v[62:65], v[94:97]
	v_mfma_f32_16x16x32_bf16 v[90:93], v[30:33], v[62:65], v[90:93]
	s_waitcnt vmcnt(2)
	s_barrier
	ds_read_b128 v[18:21], v219 offset:40960
	ds_read_b128 v[22:25], v219 offset:41216
	ds_read_b128 v[26:29], v219 offset:41472
	ds_read_b128 v[30:33], v219 offset:41728
	s_waitcnt lgkmcnt(4)
	v_mfma_f32_16x16x32_bf16 v[86:89], v[2:5], v[138:141], 0
	v_mfma_f32_16x16x32_bf16 v[82:85], v[6:9], v[138:141], 0
	v_mfma_f32_16x16x32_bf16 v[86:89], v[10:13], v[134:137], v[86:89]
	v_mfma_f32_16x16x32_bf16 v[82:85], v[14:17], v[134:137], v[82:85]
	s_waitcnt vmcnt(1)
	s_barrier
	ds_read_b128 v[2:5], v219 offset:49152
	ds_read_b128 v[6:9], v219 offset:49408
	ds_read_b128 v[10:13], v219 offset:49664
	ds_read_b128 v[14:17], v219 offset:49920
	s_waitcnt lgkmcnt(4)
	v_mfma_f32_16x16x32_bf16 v[86:89], v[18:21], v[130:133], v[86:89]
	v_mfma_f32_16x16x32_bf16 v[82:85], v[22:25], v[130:133], v[82:85]
	v_mfma_f32_16x16x32_bf16 v[86:89], v[26:29], v[62:65], v[86:89]
	v_mfma_f32_16x16x32_bf16 v[82:85], v[30:33], v[62:65], v[82:85]
	s_waitcnt vmcnt(0)
	s_barrier
	ds_read_b128 v[18:21], v219 offset:57344
	ds_read_b128 v[22:25], v219 offset:57600
	ds_read_b128 v[26:29], v219 offset:57856
	ds_read_b128 v[30:33], v219 offset:58112
	s_waitcnt lgkmcnt(4)
	v_mfma_f32_16x16x32_bf16 v[78:81], v[2:5], v[138:141], 0
	v_mfma_f32_16x16x32_bf16 v[74:77], v[6:9], v[138:141], 0
	v_mfma_f32_16x16x32_bf16 v[78:81], v[10:13], v[134:137], v[78:81]
	v_mfma_f32_16x16x32_bf16 v[74:77], v[14:17], v[134:137], v[74:77]
	s_waitcnt vmcnt(1)
	s_barrier
	ds_read_b128 v[2:5], v219 offset:0
	ds_read_b128 v[6:9], v219 offset:256
	ds_read_b128 v[10:13], v219 offset:512
	ds_read_b128 v[14:17], v219 offset:768
	s_waitcnt lgkmcnt(4)
	v_mfma_f32_16x16x32_bf16 v[78:81], v[18:21], v[130:133], v[78:81]
	v_mfma_f32_16x16x32_bf16 v[74:77], v[22:25], v[130:133], v[74:77]
	v_mfma_f32_16x16x32_bf16 v[78:81], v[26:29], v[62:65], v[78:81]
	v_mfma_f32_16x16x32_bf16 v[74:77], v[30:33], v[62:65], v[74:77]
	s_cmp_eq_u32 s73, 0
	s_cbranch_scc1 .Lrg_k_B_end
	s_waitcnt vmcnt(0)
	s_barrier
	ds_read_b128 v[18:21], v219 offset:8192
	ds_read_b128 v[22:25], v219 offset:8448
	ds_read_b128 v[26:29], v219 offset:8704
	ds_read_b128 v[30:33], v219 offset:8960
	s_waitcnt lgkmcnt(4)
	v_mfma_f32_16x16x32_bf16 v[70:73], v[2:5], v[138:141], 0
	v_mfma_f32_16x16x32_bf16 v[66:69], v[6:9], v[138:141], 0
	v_mfma_f32_16x16x32_bf16 v[70:73], v[10:13], v[134:137], v[70:73]
	v_mfma_f32_16x16x32_bf16 v[66:69], v[14:17], v[134:137], v[66:69]
	s_waitcnt lgkmcnt(0)
	v_mfma_f32_16x16x32_bf16 v[70:73], v[18:21], v[130:133], v[70:73]
	v_mfma_f32_16x16x32_bf16 v[66:69], v[22:25], v[130:133], v[66:69]
	v_mfma_f32_16x16x32_bf16 v[70:73], v[26:29], v[62:65], v[70:73]
	v_mfma_f32_16x16x32_bf16 v[66:69], v[30:33], v[62:65], v[66:69]
